# mfma_serpentine_all_gemms
# speedup vs baseline: 1.0285x; 1.0044x over previous
; #define PG8_STAGE(bufoff, gbase, voff) do { _Pragma("unroll") for (int _i = 0; _i < 2; ++_i) \
;         __builtin_amdgcn_global_load_lds((const unsigned*)((const char*)(gbase) + (voff)[_i]), (PG8_LAS unsigned*)(lds + (bufoff) + ldsw + _i * 8192), 16, 0, 0); } while (0)
; #define PG8_LDA(dst, b, h) do { _Pragma("unroll") for (int m = 0; m < 4; ++m) _Pragma("unroll") for (int k = 0; k < 2; ++k) dst[m][k] = *(const PG8_LAS bf16x8*)(lds + PG8_SA(b, h) + aoff + m * 2048 + k * 1024); } while (0)
; #define PG8_LDB(dst, b, h) do { _Pragma("unroll") for (int n = 0; n < 2; ++n) _Pragma("unroll") for (int k = 0; k < 2; ++k) dst[n][k] = *(const PG8_LAS bf16x8*)(lds + PG8_SB(b, h) + boff + n * 2048 + k * 1024); } while (0)
; #define PG8_MMA(ai, bj, At, Bt) do { __builtin_amdgcn_s_setprio(1); _Pragma("unroll") for (int m = 0; m < 4; ++m) _Pragma("unroll") for (int n = 0; n < 2; ++n) _Pragma("unroll") for (int k = 0; k < 2; ++k) \
;         acc[ai][bj][m][n] = __builtin_amdgcn_mfma_f32_16x16x32_bf16(Bt[n][k], At[m][k], acc[ai][bj][m][n], 0, 0, 0); __builtin_amdgcn_s_setprio(0); } while (0)
; #define PG8_WAIT_V(n) asm volatile("s_waitcnt vmcnt(" #n ")" ::: "memory")
; #define PG8_WAIT_L(n) asm volatile("s_waitcnt lgkmcnt(" #n ")" ::: "memory")
; #define PG8_BAR __builtin_amdgcn_s_barrier()
; #define PG8_SCHED __builtin_amdgcn_sched_barrier(0)
; template <class Epi, class Sched, bool ALIGN_EPI = false, bool SP2 = false>
; __device__ __forceinline__ void gemm_phase(PG8_LAS unsigned char* lds, const Gemm g, const Sched& S, const Epi& E) {
;     ...
;             PG8_LDB(B0, 0, 0); PG8_LDB(B1, 0, 1); PG8_SCHED; PG8_LDA(At, 0, 0); PG8_STAGE(PG8_SA(1, 1), a1 + hstep, voffA);
;             PG8_WAIT_V(8); PG8_WAIT_L(0); PG8_BAR; PG8_MMA(0, 0, At, B0); PG8_MMA(0, 1, At, B1); PG8_BAR; PG8_SCHED;
;             PG8_LDA(At, 0, 1); PG8_STAGE(PG8_SB(0, 0), b2, voffB); PG8_STAGE(PG8_SB(0, 1), b2 + hstep, voffB); PG8_STAGE(PG8_SA(0, 0), a2, voffA);
;             PG8_WAIT_V(8); PG8_WAIT_L(0); PG8_BAR; PG8_MMA(1, 0, At, B0); PG8_MMA(1, 1, At, B1); PG8_BAR; PG8_SCHED;
.LBB0_91:
	ds_read_b128 v[156:159], v152
	ds_read_b128 v[160:163], v152 offset:1024
	ds_read_b128 v[164:167], v152 offset:2048
	ds_read_b128 v[168:171], v152 offset:3072
	ds_read_b128 v[172:175], v153
	ds_read_b128 v[176:179], v153 offset:1024
	ds_read_b128 v[180:183], v153 offset:2048
	ds_read_b128 v[186:189], v153 offset:3072
	s_add_u32 s34, s30, 0xfff80080
	s_addc_u32 s35, s31, -1
	s_cmp_eq_u32 s25, 28
	s_cselect_b32 s37, s5, s35
	s_cselect_b32 s36, s7, s34
	s_cselect_b32 s35, s8, s23
	s_cselect_b32 s34, s9, s12
	v_lshl_add_u64 v[146:147], s[30:31], 0, v[138:139]
	s_add_i32 m0, s40, 0xc000
	ds_read_b128 v[190:193], v154
	ds_read_b128 v[194:197], v154 offset:1024
	ds_read_b128 v[198:201], v154 offset:2048
	ds_read_b128 v[202:205], v154 offset:3072
	ds_read_b128 v[206:209], v154 offset:4096
	ds_read_b128 v[210:213], v154 offset:5120
	ds_read_b128 v[214:217], v154 offset:6144
	ds_read_b128 v[218:221], v154 offset:7168
	global_load_lds_dwordx4 v[146:147], off
	v_lshl_add_u64 v[146:147], s[30:31], 0, v[140:141]
	s_add_i32 m0, s40, 0xe000
	s_nop 0
	global_load_lds_dwordx4 v[146:147], off
	s_waitcnt vmcnt(8)
	s_waitcnt lgkmcnt(0)
	s_barrier
	s_setprio 1
	s_waitcnt lgkmcnt(0)
	v_mfma_f32_16x16x32_bf16 v[124:127], v[156:159], v[190:193], v[124:127]
	v_mfma_f32_16x16x32_bf16 v[124:127], v[160:163], v[194:197], v[124:127]
	v_mfma_f32_16x16x32_bf16 v[120:123], v[168:171], v[194:197], v[120:123]
	v_mfma_f32_16x16x32_bf16 v[120:123], v[164:167], v[190:193], v[120:123]
	v_mfma_f32_16x16x32_bf16 v[104:107], v[164:167], v[198:201], v[104:107]
	v_mfma_f32_16x16x32_bf16 v[104:107], v[168:171], v[202:205], v[104:107]
	v_mfma_f32_16x16x32_bf16 v[108:111], v[160:163], v[202:205], v[108:111]
	v_mfma_f32_16x16x32_bf16 v[108:111], v[156:159], v[198:201], v[108:111]
	v_mfma_f32_16x16x32_bf16 v[92:95], v[156:159], v[206:209], v[92:95]
	v_mfma_f32_16x16x32_bf16 v[92:95], v[160:163], v[210:213], v[92:95]
	v_mfma_f32_16x16x32_bf16 v[88:91], v[168:171], v[210:213], v[88:91]
	v_mfma_f32_16x16x32_bf16 v[88:91], v[164:167], v[206:209], v[88:91]
	v_mfma_f32_16x16x32_bf16 v[72:75], v[164:167], v[214:217], v[72:75]
	v_mfma_f32_16x16x32_bf16 v[72:75], v[168:171], v[218:221], v[72:75]
	v_mfma_f32_16x16x32_bf16 v[76:79], v[160:163], v[218:221], v[76:79]
	v_mfma_f32_16x16x32_bf16 v[76:79], v[156:159], v[214:217], v[76:79]
	s_setprio 0
	s_setprio 1
	v_mfma_f32_16x16x32_bf16 v[116:119], v[172:175], v[190:193], v[116:119]
	v_mfma_f32_16x16x32_bf16 v[116:119], v[176:179], v[194:197], v[116:119]
	v_mfma_f32_16x16x32_bf16 v[112:115], v[186:189], v[194:197], v[112:115]
	v_mfma_f32_16x16x32_bf16 v[112:115], v[180:183], v[190:193], v[112:115]
	v_mfma_f32_16x16x32_bf16 v[96:99], v[180:183], v[198:201], v[96:99]
	v_mfma_f32_16x16x32_bf16 v[96:99], v[186:189], v[202:205], v[96:99]
	v_mfma_f32_16x16x32_bf16 v[100:103], v[176:179], v[202:205], v[100:103]
	v_mfma_f32_16x16x32_bf16 v[100:103], v[172:175], v[198:201], v[100:103]
	v_mfma_f32_16x16x32_bf16 v[84:87], v[172:175], v[206:209], v[84:87]
	v_mfma_f32_16x16x32_bf16 v[84:87], v[176:179], v[210:213], v[84:87]
	v_mfma_f32_16x16x32_bf16 v[80:83], v[186:189], v[210:213], v[80:83]
	v_mfma_f32_16x16x32_bf16 v[80:83], v[180:183], v[206:209], v[80:83]
	v_mfma_f32_16x16x32_bf16 v[64:67], v[180:183], v[214:217], v[64:67]
	v_mfma_f32_16x16x32_bf16 v[64:67], v[186:189], v[218:221], v[64:67]
	v_mfma_f32_16x16x32_bf16 v[68:71], v[176:179], v[218:221], v[68:71]
	v_mfma_f32_16x16x32_bf16 v[68:71], v[172:175], v[214:217], v[68:71]
	s_setprio 0
	s_barrier
	s_add_i32 s56, s97, s39
	v_lshl_add_u64 v[146:147], s[34:35], 0, v[130:131]
	s_mov_b32 m0, s56
	ds_read_b128 v[190:193], v154 offset:16384
	ds_read_b128 v[194:197], v154 offset:17408
	ds_read_b128 v[198:201], v154 offset:18432
	ds_read_b128 v[202:205], v154 offset:19456
	ds_read_b128 v[206:209], v154 offset:20480
	ds_read_b128 v[210:213], v154 offset:21504
	ds_read_b128 v[214:217], v154 offset:22528
	ds_read_b128 v[218:221], v154 offset:23552
	global_load_lds_dwordx4 v[146:147], off
	s_add_i32 m0, s56, 0x2000
	s_add_u32 s56, s34, 0x80000
	v_lshl_add_u64 v[222:223], s[34:35], 0, v[134:135]
	s_addc_u32 s57, s35, 0
	s_add_i32 s58, s73, s39
	global_load_lds_dwordx4 v[222:223], off
	v_lshl_add_u64 v[224:225], s[56:57], 0, v[130:131]
	s_mov_b32 m0, s58
	v_lshl_add_u64 v[226:227], s[36:37], 0, v[132:133]
	global_load_lds_dwordx4 v[224:225], off
	v_lshl_add_u64 v[224:225], s[56:57], 0, v[134:135]
	s_add_i32 m0, s58, 0x2000
	s_nop 0
	global_load_lds_dwordx4 v[224:225], off
	v_lshl_add_u64 v[224:225], s[36:37], 0, v[128:129]
	s_mov_b32 m0, s40
	s_nop 0
	global_load_lds_dwordx4 v[224:225], off
	s_mov_b32 m0, s41
	s_nop 0
	global_load_lds_dwordx4 v[226:227], off
	s_waitcnt vmcnt(8)
	s_waitcnt lgkmcnt(0)
	s_barrier
; #define PG8_STAGE(bufoff, gbase, voff) do { _Pragma("unroll") for (int _i = 0; _i < 2; ++_i) \
;         __builtin_amdgcn_global_load_lds((const unsigned*)((const char*)(gbase) + (voff)[_i]), (PG8_LAS unsigned*)(lds + (bufoff) + ldsw + _i * 8192), 16, 0, 0); } while (0)
; #define PG8_LDA(dst, b, h) do { _Pragma("unroll") for (int m = 0; m < 4; ++m) _Pragma("unroll") for (int k = 0; k < 2; ++k) dst[m][k] = *(const PG8_LAS bf16x8*)(lds + PG8_SA(b, h) + aoff + m * 2048 + k * 1024); } while (0)
; #define PG8_LDB(dst, b, h) do { _Pragma("unroll") for (int n = 0; n < 2; ++n) _Pragma("unroll") for (int k = 0; k < 2; ++k) dst[n][k] = *(const PG8_LAS bf16x8*)(lds + PG8_SB(b, h) + boff + n * 2048 + k * 1024); } while (0)
; #define PG8_MMA(ai, bj, At, Bt) do { __builtin_amdgcn_s_setprio(1); _Pragma("unroll") for (int m = 0; m < 4; ++m) _Pragma("unroll") for (int n = 0; n < 2; ++n) _Pragma("unroll") for (int k = 0; k < 2; ++k) \
;         acc[ai][bj][m][n] = __builtin_amdgcn_mfma_f32_16x16x32_bf16(Bt[n][k], At[m][k], acc[ai][bj][m][n], 0, 0, 0); __builtin_amdgcn_s_setprio(0); } while (0)
; #define PG8_WAIT_V(n) asm volatile("s_waitcnt vmcnt(" #n ")" ::: "memory")
; #define PG8_WAIT_L(n) asm volatile("s_waitcnt lgkmcnt(" #n ")" ::: "memory")
; #define PG8_BAR __builtin_amdgcn_s_barrier()
; #define PG8_SCHED __builtin_amdgcn_sched_barrier(0)
; template <class Epi, class Sched, bool ALIGN_EPI = false, bool SP2 = false>
; __device__ __forceinline__ void gemm_phase(PG8_LAS unsigned char* lds, const Gemm g, const Sched& S, const Epi& E) {
;     ...
;             PG8_WAIT_V(8); PG8_WAIT_L(0); PG8_BAR; PG8_MMA(1, 0, At, B0); PG8_MMA(1, 1, At, B1); PG8_BAR; PG8_SCHED;
;             PG8_LDB(B0, 1, 0); PG8_LDB(B1, 1, 1); PG8_SCHED; PG8_LDA(At, 1, 0); PG8_STAGE(PG8_SA(0, 1), a2 + hstep, voffA);
;             PG8_WAIT_V(8); PG8_WAIT_L(0); PG8_BAR; PG8_MMA(0, 0, At, B0); PG8_MMA(0, 1, At, B1); PG8_BAR; PG8_SCHED;
;             PG8_LDA(At, 1, 1); PG8_STAGE(PG8_SB(1, 0), b3, voffB); PG8_STAGE(PG8_SB(1, 1), b3 + hstep, voffB); PG8_STAGE(PG8_SA(1, 0), a3, voffA);
	s_setprio 1
	s_waitcnt lgkmcnt(0)
	v_mfma_f32_16x16x32_bf16 v[60:63], v[156:159], v[190:193], v[60:63]
	v_mfma_f32_16x16x32_bf16 v[60:63], v[160:163], v[194:197], v[60:63]
	v_mfma_f32_16x16x32_bf16 v[56:59], v[168:171], v[194:197], v[56:59]
	v_mfma_f32_16x16x32_bf16 v[56:59], v[164:167], v[190:193], v[56:59]
	v_mfma_f32_16x16x32_bf16 v[40:43], v[164:167], v[198:201], v[40:43]
	v_mfma_f32_16x16x32_bf16 v[40:43], v[168:171], v[202:205], v[40:43]
	v_mfma_f32_16x16x32_bf16 v[44:47], v[160:163], v[202:205], v[44:47]
	v_mfma_f32_16x16x32_bf16 v[44:47], v[156:159], v[198:201], v[44:47]
	v_mfma_f32_16x16x32_bf16 v[28:31], v[156:159], v[206:209], v[28:31]
	v_mfma_f32_16x16x32_bf16 v[28:31], v[160:163], v[210:213], v[28:31]
	v_mfma_f32_16x16x32_bf16 v[24:27], v[168:171], v[210:213], v[24:27]
	v_mfma_f32_16x16x32_bf16 v[24:27], v[164:167], v[206:209], v[24:27]
	v_mfma_f32_16x16x32_bf16 v[8:11], v[164:167], v[214:217], v[8:11]
	v_mfma_f32_16x16x32_bf16 v[8:11], v[168:171], v[218:221], v[8:11]
	v_mfma_f32_16x16x32_bf16 v[12:15], v[160:163], v[218:221], v[12:15]
	v_mfma_f32_16x16x32_bf16 v[12:15], v[156:159], v[214:217], v[12:15]
	s_setprio 0
	s_setprio 1
	v_mfma_f32_16x16x32_bf16 v[52:55], v[172:175], v[190:193], v[52:55]
	v_mfma_f32_16x16x32_bf16 v[52:55], v[176:179], v[194:197], v[52:55]
	v_mfma_f32_16x16x32_bf16 v[48:51], v[186:189], v[194:197], v[48:51]
	v_mfma_f32_16x16x32_bf16 v[48:51], v[180:183], v[190:193], v[48:51]
	v_mfma_f32_16x16x32_bf16 v[32:35], v[180:183], v[198:201], v[32:35]
	v_mfma_f32_16x16x32_bf16 v[32:35], v[186:189], v[202:205], v[32:35]
	v_mfma_f32_16x16x32_bf16 v[36:39], v[176:179], v[202:205], v[36:39]
	v_mfma_f32_16x16x32_bf16 v[36:39], v[172:175], v[198:201], v[36:39]
	v_mfma_f32_16x16x32_bf16 v[20:23], v[172:175], v[206:209], v[20:23]
	v_mfma_f32_16x16x32_bf16 v[20:23], v[176:179], v[210:213], v[20:23]
	v_mfma_f32_16x16x32_bf16 v[16:19], v[186:189], v[210:213], v[16:19]
	v_mfma_f32_16x16x32_bf16 v[16:19], v[180:183], v[206:209], v[16:19]
	v_mfma_f32_16x16x32_bf16 v[0:3], v[180:183], v[214:217], v[0:3]
	v_mfma_f32_16x16x32_bf16 v[0:3], v[186:189], v[218:221], v[0:3]
	v_mfma_f32_16x16x32_bf16 v[4:7], v[176:179], v[218:221], v[4:7]
	v_mfma_f32_16x16x32_bf16 v[4:7], v[172:175], v[214:217], v[4:7]
	s_setprio 0
	s_barrier
	s_add_i32 s56, 0, 0x18000
	v_add_u32_e32 v136, s56, v150
	s_add_i32 s57, 0, 0x1c000
	ds_read_b128 v[156:159], v136
	ds_read_b128 v[160:163], v136 offset:1024
	ds_read_b128 v[164:167], v136 offset:2048
	ds_read_b128 v[168:171], v136 offset:3072
	v_add_u32_e32 v136, s57, v150
	ds_read_b128 v[172:175], v136
	ds_read_b128 v[176:179], v136 offset:1024
	ds_read_b128 v[180:183], v136 offset:2048
	ds_read_b128 v[186:189], v136 offset:3072
	s_add_u32 s36, s36, 0x80000
	s_addc_u32 s37, s37, 0
	s_mov_b32 m0, s42
	v_lshl_add_u64 v[228:229], s[36:37], 0, v[128:129]
	ds_read_b128 v[190:193], v154 offset:32768
	ds_read_b128 v[194:197], v154 offset:33792
	ds_read_b128 v[198:201], v154 offset:34816
	ds_read_b128 v[202:205], v154 offset:35840
	ds_read_b128 v[206:209], v154 offset:36864
	ds_read_b128 v[210:213], v154 offset:37888
	ds_read_b128 v[214:217], v154 offset:38912
	ds_read_b128 v[218:221], v154 offset:39936
	global_load_lds_dwordx4 v[228:229], off
	v_lshl_add_u64 v[228:229], s[36:37], 0, v[132:133]
	s_mov_b32 m0, s43
	s_nop 0
	global_load_lds_dwordx4 v[228:229], off
	s_waitcnt vmcnt(8)
	s_waitcnt lgkmcnt(0)
	s_barrier
	s_setprio 1
	s_waitcnt lgkmcnt(0)
	v_mfma_f32_16x16x32_bf16 v[124:127], v[156:159], v[190:193], v[124:127]
	v_mfma_f32_16x16x32_bf16 v[124:127], v[160:163], v[194:197], v[124:127]
	v_mfma_f32_16x16x32_bf16 v[120:123], v[168:171], v[194:197], v[120:123]
	v_mfma_f32_16x16x32_bf16 v[120:123], v[164:167], v[190:193], v[120:123]
	v_mfma_f32_16x16x32_bf16 v[104:107], v[164:167], v[198:201], v[104:107]
	v_mfma_f32_16x16x32_bf16 v[104:107], v[168:171], v[202:205], v[104:107]
	v_mfma_f32_16x16x32_bf16 v[108:111], v[160:163], v[202:205], v[108:111]
	v_mfma_f32_16x16x32_bf16 v[108:111], v[156:159], v[198:201], v[108:111]
	v_mfma_f32_16x16x32_bf16 v[92:95], v[156:159], v[206:209], v[92:95]
	v_mfma_f32_16x16x32_bf16 v[92:95], v[160:163], v[210:213], v[92:95]
	v_mfma_f32_16x16x32_bf16 v[88:91], v[168:171], v[210:213], v[88:91]
	v_mfma_f32_16x16x32_bf16 v[88:91], v[164:167], v[206:209], v[88:91]
	v_mfma_f32_16x16x32_bf16 v[72:75], v[164:167], v[214:217], v[72:75]
	v_mfma_f32_16x16x32_bf16 v[72:75], v[168:171], v[218:221], v[72:75]
	v_mfma_f32_16x16x32_bf16 v[76:79], v[160:163], v[218:221], v[76:79]
	v_mfma_f32_16x16x32_bf16 v[76:79], v[156:159], v[214:217], v[76:79]
	s_setprio 0
	s_setprio 1
	v_mfma_f32_16x16x32_bf16 v[116:119], v[172:175], v[190:193], v[116:119]
	v_mfma_f32_16x16x32_bf16 v[116:119], v[176:179], v[194:197], v[116:119]
	v_mfma_f32_16x16x32_bf16 v[112:115], v[186:189], v[194:197], v[112:115]
	v_mfma_f32_16x16x32_bf16 v[112:115], v[180:183], v[190:193], v[112:115]
	v_mfma_f32_16x16x32_bf16 v[96:99], v[180:183], v[198:201], v[96:99]
	v_mfma_f32_16x16x32_bf16 v[96:99], v[186:189], v[202:205], v[96:99]
	v_mfma_f32_16x16x32_bf16 v[100:103], v[176:179], v[202:205], v[100:103]
	v_mfma_f32_16x16x32_bf16 v[100:103], v[172:175], v[198:201], v[100:103]
	v_mfma_f32_16x16x32_bf16 v[84:87], v[172:175], v[206:209], v[84:87]
	v_mfma_f32_16x16x32_bf16 v[84:87], v[176:179], v[210:213], v[84:87]
	v_mfma_f32_16x16x32_bf16 v[80:83], v[186:189], v[210:213], v[80:83]
	v_mfma_f32_16x16x32_bf16 v[80:83], v[180:183], v[206:209], v[80:83]
	v_mfma_f32_16x16x32_bf16 v[64:67], v[180:183], v[214:217], v[64:67]
	v_mfma_f32_16x16x32_bf16 v[64:67], v[186:189], v[218:221], v[64:67]
	v_mfma_f32_16x16x32_bf16 v[68:71], v[176:179], v[218:221], v[68:71]
	v_mfma_f32_16x16x32_bf16 v[68:71], v[172:175], v[214:217], v[68:71]
	s_setprio 0
	s_barrier
; #define PG8_STAGE(bufoff, gbase, voff) do { _Pragma("unroll") for (int _i = 0; _i < 2; ++_i) \
;         __builtin_amdgcn_global_load_lds((const unsigned*)((const char*)(gbase) + (voff)[_i]), (PG8_LAS unsigned*)(lds + (bufoff) + ldsw + _i * 8192), 16, 0, 0); } while (0)
; #define PG8_LDA(dst, b, h) do { _Pragma("unroll") for (int m = 0; m < 4; ++m) _Pragma("unroll") for (int k = 0; k < 2; ++k) dst[m][k] = *(const PG8_LAS bf16x8*)(lds + PG8_SA(b, h) + aoff + m * 2048 + k * 1024); } while (0)
; #define PG8_MMA(ai, bj, At, Bt) do { __builtin_amdgcn_s_setprio(1); _Pragma("unroll") for (int m = 0; m < 4; ++m) _Pragma("unroll") for (int n = 0; n < 2; ++n) _Pragma("unroll") for (int k = 0; k < 2; ++k) \
;         acc[ai][bj][m][n] = __builtin_amdgcn_mfma_f32_16x16x32_bf16(Bt[n][k], At[m][k], acc[ai][bj][m][n], 0, 0, 0); __builtin_amdgcn_s_setprio(0); } while (0)
; #define PG8_WAIT_V(n) asm volatile("s_waitcnt vmcnt(" #n ")" ::: "memory")
; #define PG8_WAIT_L(n) asm volatile("s_waitcnt lgkmcnt(" #n ")" ::: "memory")
; #define PG8_BAR __builtin_amdgcn_s_barrier()
; #define PG8_SCHED __builtin_amdgcn_sched_barrier(0)
; template <class Epi, class Sched, bool ALIGN_EPI = false, bool SP2 = false>
; __device__ __forceinline__ void gemm_phase(PG8_LAS unsigned char* lds, const Gemm g, const Sched& S, const Epi& E) {
;     ...
;         for (int t = 0; t < nt; t += 2) {
;             const bool last = (t == nt - 2);
;             const char* a1 = cA + (size_t)(t + 1) * kstep;
;             const char* a2 = last ? nA : cA + (size_t)(t + 2) * kstep; const char* b2 = last ? nB : cB + (size_t)(t + 2) * kstep;
;             const char* a3 = a2 + kstep; const char* b3 = b2 + kstep;
;     ...
;             PG8_LDA(At, 1, 1); PG8_STAGE(PG8_SB(1, 0), b3, voffB); PG8_STAGE(PG8_SB(1, 1), b3 + hstep, voffB); PG8_STAGE(PG8_SA(1, 0), a3, voffA);
;             PG8_WAIT_V(8); PG8_WAIT_L(0); PG8_BAR; PG8_MMA(1, 0, At, B0); PG8_MMA(1, 1, At, B1); PG8_BAR; PG8_SCHED;
	s_add_i32 s36, s56, s39
	v_lshl_add_u64 v[146:147], v[146:147], 0, s[16:17]
	s_mov_b32 m0, s36
	ds_read_b128 v[190:193], v154 offset:49152
	ds_read_b128 v[194:197], v154 offset:50176
	ds_read_b128 v[198:201], v154 offset:51200
	ds_read_b128 v[202:205], v154 offset:52224
	ds_read_b128 v[206:209], v154 offset:53248
	ds_read_b128 v[210:213], v154 offset:54272
	ds_read_b128 v[214:217], v154 offset:55296
	ds_read_b128 v[218:221], v154 offset:56320
	global_load_lds_dwordx4 v[146:147], off
	s_add_i32 m0, s36, 0x2000
	s_add_u32 s34, s34, 0x80080
	v_lshl_add_u64 v[146:147], v[222:223], 0, s[16:17]
	s_addc_u32 s35, s35, 0
	s_add_i32 s36, s57, s39
	global_load_lds_dwordx4 v[146:147], off
	v_lshl_add_u64 v[146:147], s[34:35], 0, v[130:131]
	s_mov_b32 m0, s36
	s_nop 0
	global_load_lds_dwordx4 v[146:147], off
	v_lshl_add_u64 v[146:147], s[34:35], 0, v[134:135]
	s_add_i32 m0, s36, 0x2000
	s_nop 0
	global_load_lds_dwordx4 v[146:147], off
	v_lshl_add_u64 v[146:147], v[224:225], 0, s[16:17]
	s_mov_b32 m0, s75
	s_nop 0
	global_load_lds_dwordx4 v[146:147], off
	v_lshl_add_u64 v[146:147], v[226:227], 0, s[16:17]
	s_mov_b32 m0, s91
	s_nop 0
	global_load_lds_dwordx4 v[146:147], off
	s_waitcnt vmcnt(8)
	s_waitcnt lgkmcnt(0)
	s_barrier
	s_setprio 1
	s_waitcnt lgkmcnt(0)
	v_mfma_f32_16x16x32_bf16 v[60:63], v[156:159], v[190:193], v[60:63]
	v_mfma_f32_16x16x32_bf16 v[60:63], v[160:163], v[194:197], v[60:63]
	v_mfma_f32_16x16x32_bf16 v[56:59], v[168:171], v[194:197], v[56:59]
	v_mfma_f32_16x16x32_bf16 v[56:59], v[164:167], v[190:193], v[56:59]
	v_mfma_f32_16x16x32_bf16 v[40:43], v[164:167], v[198:201], v[40:43]
	v_mfma_f32_16x16x32_bf16 v[40:43], v[168:171], v[202:205], v[40:43]
	v_mfma_f32_16x16x32_bf16 v[44:47], v[160:163], v[202:205], v[44:47]
	v_mfma_f32_16x16x32_bf16 v[44:47], v[156:159], v[198:201], v[44:47]
	v_mfma_f32_16x16x32_bf16 v[28:31], v[156:159], v[206:209], v[28:31]
	v_mfma_f32_16x16x32_bf16 v[28:31], v[160:163], v[210:213], v[28:31]
	v_mfma_f32_16x16x32_bf16 v[24:27], v[168:171], v[210:213], v[24:27]
	v_mfma_f32_16x16x32_bf16 v[24:27], v[164:167], v[206:209], v[24:27]
	v_mfma_f32_16x16x32_bf16 v[8:11], v[164:167], v[214:217], v[8:11]
	v_mfma_f32_16x16x32_bf16 v[8:11], v[168:171], v[218:221], v[8:11]
	v_mfma_f32_16x16x32_bf16 v[12:15], v[160:163], v[218:221], v[12:15]
	v_mfma_f32_16x16x32_bf16 v[12:15], v[156:159], v[214:217], v[12:15]
	s_setprio 0
	s_setprio 1
	v_mfma_f32_16x16x32_bf16 v[52:55], v[172:175], v[190:193], v[52:55]
	v_mfma_f32_16x16x32_bf16 v[52:55], v[176:179], v[194:197], v[52:55]
	v_mfma_f32_16x16x32_bf16 v[48:51], v[186:189], v[194:197], v[48:51]
	v_mfma_f32_16x16x32_bf16 v[48:51], v[180:183], v[190:193], v[48:51]
	v_mfma_f32_16x16x32_bf16 v[32:35], v[180:183], v[198:201], v[32:35]
	v_mfma_f32_16x16x32_bf16 v[32:35], v[186:189], v[202:205], v[32:35]
	v_mfma_f32_16x16x32_bf16 v[36:39], v[176:179], v[202:205], v[36:39]
	v_mfma_f32_16x16x32_bf16 v[36:39], v[172:175], v[198:201], v[36:39]
	v_mfma_f32_16x16x32_bf16 v[20:23], v[172:175], v[206:209], v[20:23]
	v_mfma_f32_16x16x32_bf16 v[20:23], v[176:179], v[210:213], v[20:23]
	v_mfma_f32_16x16x32_bf16 v[16:19], v[186:189], v[210:213], v[16:19]
	v_mfma_f32_16x16x32_bf16 v[16:19], v[180:183], v[206:209], v[16:19]
	v_mfma_f32_16x16x32_bf16 v[0:3], v[180:183], v[214:217], v[0:3]
	v_mfma_f32_16x16x32_bf16 v[0:3], v[186:189], v[218:221], v[0:3]
	v_mfma_f32_16x16x32_bf16 v[4:7], v[176:179], v[218:221], v[4:7]
	v_mfma_f32_16x16x32_bf16 v[4:7], v[172:175], v[214:217], v[4:7]
	s_setprio 0
	s_barrier
	s_add_i32 s25, s25, 2
	s_add_u32 s30, s30, 0x100
	s_addc_u32 s31, s31, 0
	s_add_u32 s12, s12, 0x100
	s_addc_u32 s23, s23, 0
	s_cmp_gt_u32 s25, 29
	s_cbranch_scc0 .LBB0_91
	s_and_b64 vcc, exec, s[18:19]
	s_cbranch_vccz .LBB0_94
	s_barrier

; #define PG8_STAGE(bufoff, gbase, voff) do { _Pragma("unroll") for (int _i = 0; _i < 2; ++_i) \
;         __builtin_amdgcn_global_load_lds((const unsigned*)((const char*)(gbase) + (voff)[_i]), (PG8_LAS unsigned*)(lds + (bufoff) + ldsw + _i * 8192), 16, 0, 0); } while (0)
; #define PG8_LDA(dst, b, h) do { _Pragma("unroll") for (int m = 0; m < 4; ++m) _Pragma("unroll") for (int k = 0; k < 2; ++k) dst[m][k] = *(const PG8_LAS bf16x8*)(lds + PG8_SA(b, h) + aoff + m * 2048 + k * 1024); } while (0)
; #define PG8_LDB(dst, b, h) do { _Pragma("unroll") for (int n = 0; n < 2; ++n) _Pragma("unroll") for (int k = 0; k < 2; ++k) dst[n][k] = *(const PG8_LAS bf16x8*)(lds + PG8_SB(b, h) + boff + n * 2048 + k * 1024); } while (0)
; #define PG8_MMA(ai, bj, At, Bt) do { __builtin_amdgcn_s_setprio(1); _Pragma("unroll") for (int m = 0; m < 4; ++m) _Pragma("unroll") for (int n = 0; n < 2; ++n) _Pragma("unroll") for (int k = 0; k < 2; ++k) \
;         acc[ai][bj][m][n] = __builtin_amdgcn_mfma_f32_16x16x32_bf16(Bt[n][k], At[m][k], acc[ai][bj][m][n], 0, 0, 0); __builtin_amdgcn_s_setprio(0); } while (0)
; #define PG8_WAIT_V(n) asm volatile("s_waitcnt vmcnt(" #n ")" ::: "memory")
; #define PG8_WAIT_L(n) asm volatile("s_waitcnt lgkmcnt(" #n ")" ::: "memory")
; #define PG8_BAR __builtin_amdgcn_s_barrier()
; #define PG8_SCHED __builtin_amdgcn_sched_barrier(0)
; template <class Epi, class Sched, bool ALIGN_EPI = false, bool SP2 = false>
; __device__ __forceinline__ void gemm_phase(PG8_LAS unsigned char* lds, const Gemm g, const Sched& S, const Epi& E) {
;     ...
;             PG8_LDB(B0, 0, 0); PG8_LDB(B1, 0, 1); PG8_SCHED; PG8_LDA(At, 0, 0); PG8_STAGE(PG8_SA(1, 1), a1 + hstep, voffA);
;             PG8_WAIT_V(8); PG8_WAIT_L(0); PG8_BAR; PG8_MMA(0, 0, At, B0); PG8_MMA(0, 1, At, B1); PG8_BAR; PG8_SCHED;
;             PG8_LDA(At, 0, 1); PG8_STAGE(PG8_SB(0, 0), b2, voffB); PG8_STAGE(PG8_SB(0, 1), b2 + hstep, voffB); PG8_STAGE(PG8_SA(0, 0), a2, voffA);
;             PG8_WAIT_V(8); PG8_WAIT_L(0); PG8_BAR; PG8_MMA(1, 0, At, B0); PG8_MMA(1, 1, At, B1); PG8_BAR; PG8_SCHED;
.LBB0_692:
	ds_read_b128 v[128:131], v213
	ds_read_b128 v[132:135], v213 offset:1024
	ds_read_b128 v[136:139], v213 offset:2048
	ds_read_b128 v[140:143], v213 offset:3072
	ds_read_b128 v[144:147], v214
	ds_read_b128 v[148:151], v214 offset:1024
	ds_read_b128 v[152:155], v214 offset:2048
	ds_read_b128 v[156:159], v214 offset:3072
	s_add_u32 s28, s26, 0xfff80080
	s_addc_u32 s29, s27, -1
	s_cmp_eq_u32 s47, 28
	s_cselect_b32 s31, s17, s29
	s_cselect_b32 s30, s23, s28
	s_cselect_b32 s29, s15, s46
	s_cselect_b32 s28, s44, s45
	v_lshl_add_u64 v[222:223], s[26:27], 0, v[186:187]
	s_add_i32 m0, s25, 0xc000
	ds_read_b128 v[160:163], v215
	ds_read_b128 v[164:167], v215 offset:1024
	ds_read_b128 v[168:171], v215 offset:2048
	ds_read_b128 v[172:175], v215 offset:3072
	ds_read_b128 v[194:197], v215 offset:4096
	ds_read_b128 v[198:201], v215 offset:5120
	ds_read_b128 v[202:205], v215 offset:6144
	ds_read_b128 v[218:221], v215 offset:7168
	global_load_lds_dwordx4 v[222:223], off
	v_lshl_add_u64 v[222:223], s[26:27], 0, v[188:189]
	s_add_i32 m0, s25, 0xe000
	s_nop 0
	global_load_lds_dwordx4 v[222:223], off
	s_waitcnt vmcnt(8)
	s_waitcnt lgkmcnt(0)
	s_barrier
	s_setprio 1
	s_waitcnt lgkmcnt(0)
	v_mfma_f32_16x16x32_bf16 v[124:127], v[128:131], v[160:163], v[124:127]
	v_mfma_f32_16x16x32_bf16 v[124:127], v[132:135], v[164:167], v[124:127]
	v_mfma_f32_16x16x32_bf16 v[120:123], v[140:143], v[164:167], v[120:123]
	v_mfma_f32_16x16x32_bf16 v[120:123], v[136:139], v[160:163], v[120:123]
	v_mfma_f32_16x16x32_bf16 v[104:107], v[136:139], v[168:171], v[104:107]
	v_mfma_f32_16x16x32_bf16 v[104:107], v[140:143], v[172:175], v[104:107]
	v_mfma_f32_16x16x32_bf16 v[108:111], v[132:135], v[172:175], v[108:111]
	v_mfma_f32_16x16x32_bf16 v[108:111], v[128:131], v[168:171], v[108:111]
	v_mfma_f32_16x16x32_bf16 v[92:95], v[128:131], v[194:197], v[92:95]
	v_mfma_f32_16x16x32_bf16 v[92:95], v[132:135], v[198:201], v[92:95]
	v_mfma_f32_16x16x32_bf16 v[88:91], v[140:143], v[198:201], v[88:91]
	v_mfma_f32_16x16x32_bf16 v[88:91], v[136:139], v[194:197], v[88:91]
	v_mfma_f32_16x16x32_bf16 v[72:75], v[136:139], v[202:205], v[72:75]
	v_mfma_f32_16x16x32_bf16 v[72:75], v[140:143], v[218:221], v[72:75]
	v_mfma_f32_16x16x32_bf16 v[76:79], v[132:135], v[218:221], v[76:79]
	v_mfma_f32_16x16x32_bf16 v[76:79], v[128:131], v[202:205], v[76:79]
	s_setprio 0
	s_setprio 1
	v_mfma_f32_16x16x32_bf16 v[116:119], v[144:147], v[160:163], v[116:119]
	v_mfma_f32_16x16x32_bf16 v[116:119], v[148:151], v[164:167], v[116:119]
	v_mfma_f32_16x16x32_bf16 v[112:115], v[156:159], v[164:167], v[112:115]
	v_mfma_f32_16x16x32_bf16 v[112:115], v[152:155], v[160:163], v[112:115]
	v_mfma_f32_16x16x32_bf16 v[96:99], v[152:155], v[168:171], v[96:99]
	v_mfma_f32_16x16x32_bf16 v[96:99], v[156:159], v[172:175], v[96:99]
	v_mfma_f32_16x16x32_bf16 v[100:103], v[148:151], v[172:175], v[100:103]
	v_mfma_f32_16x16x32_bf16 v[100:103], v[144:147], v[168:171], v[100:103]
	v_mfma_f32_16x16x32_bf16 v[84:87], v[144:147], v[194:197], v[84:87]
	v_mfma_f32_16x16x32_bf16 v[84:87], v[148:151], v[198:201], v[84:87]
	v_mfma_f32_16x16x32_bf16 v[80:83], v[156:159], v[198:201], v[80:83]
	v_mfma_f32_16x16x32_bf16 v[80:83], v[152:155], v[194:197], v[80:83]
	v_mfma_f32_16x16x32_bf16 v[64:67], v[152:155], v[202:205], v[64:67]
	v_mfma_f32_16x16x32_bf16 v[64:67], v[156:159], v[218:221], v[64:67]
	v_mfma_f32_16x16x32_bf16 v[68:71], v[148:151], v[218:221], v[68:71]
	v_mfma_f32_16x16x32_bf16 v[68:71], v[144:147], v[202:205], v[68:71]
	s_setprio 0
	s_barrier
	s_add_i32 s48, s42, s3
	v_lshl_add_u64 v[222:223], s[28:29], 0, v[178:179]
	s_mov_b32 m0, s48
	ds_read_b128 v[160:163], v215 offset:16384
	ds_read_b128 v[164:167], v215 offset:17408
	ds_read_b128 v[168:171], v215 offset:18432
	ds_read_b128 v[172:175], v215 offset:19456
	ds_read_b128 v[194:197], v215 offset:20480
	ds_read_b128 v[198:201], v215 offset:21504
	ds_read_b128 v[202:205], v215 offset:22528
	ds_read_b128 v[218:221], v215 offset:23552
	global_load_lds_dwordx4 v[222:223], off
	s_add_i32 m0, s48, 0x2000
	s_add_u32 s48, s28, 0x80000
	v_lshl_add_u64 v[224:225], s[28:29], 0, v[182:183]
	s_addc_u32 s49, s29, 0
	s_add_i32 s50, s43, s3
	global_load_lds_dwordx4 v[224:225], off
	v_lshl_add_u64 v[226:227], s[48:49], 0, v[178:179]
	s_mov_b32 m0, s50
	v_lshl_add_u64 v[228:229], s[30:31], 0, v[180:181]
	global_load_lds_dwordx4 v[226:227], off
	v_lshl_add_u64 v[226:227], s[48:49], 0, v[182:183]
	s_add_i32 m0, s50, 0x2000
	s_nop 0
	global_load_lds_dwordx4 v[226:227], off
	v_lshl_add_u64 v[226:227], s[30:31], 0, v[176:177]
	s_mov_b32 m0, s25
	s_nop 0
	global_load_lds_dwordx4 v[226:227], off
	s_mov_b32 m0, s33
	s_nop 0
	global_load_lds_dwordx4 v[228:229], off
	s_waitcnt vmcnt(8)
	s_waitcnt lgkmcnt(0)
	s_barrier
; #define PG8_STAGE(bufoff, gbase, voff) do { _Pragma("unroll") for (int _i = 0; _i < 2; ++_i) \
;         __builtin_amdgcn_global_load_lds((const unsigned*)((const char*)(gbase) + (voff)[_i]), (PG8_LAS unsigned*)(lds + (bufoff) + ldsw + _i * 8192), 16, 0, 0); } while (0)
; #define PG8_LDA(dst, b, h) do { _Pragma("unroll") for (int m = 0; m < 4; ++m) _Pragma("unroll") for (int k = 0; k < 2; ++k) dst[m][k] = *(const PG8_LAS bf16x8*)(lds + PG8_SA(b, h) + aoff + m * 2048 + k * 1024); } while (0)
; #define PG8_LDB(dst, b, h) do { _Pragma("unroll") for (int n = 0; n < 2; ++n) _Pragma("unroll") for (int k = 0; k < 2; ++k) dst[n][k] = *(const PG8_LAS bf16x8*)(lds + PG8_SB(b, h) + boff + n * 2048 + k * 1024); } while (0)
; #define PG8_MMA(ai, bj, At, Bt) do { __builtin_amdgcn_s_setprio(1); _Pragma("unroll") for (int m = 0; m < 4; ++m) _Pragma("unroll") for (int n = 0; n < 2; ++n) _Pragma("unroll") for (int k = 0; k < 2; ++k) \
;         acc[ai][bj][m][n] = __builtin_amdgcn_mfma_f32_16x16x32_bf16(Bt[n][k], At[m][k], acc[ai][bj][m][n], 0, 0, 0); __builtin_amdgcn_s_setprio(0); } while (0)
; #define PG8_WAIT_V(n) asm volatile("s_waitcnt vmcnt(" #n ")" ::: "memory")
; #define PG8_WAIT_L(n) asm volatile("s_waitcnt lgkmcnt(" #n ")" ::: "memory")
; #define PG8_BAR __builtin_amdgcn_s_barrier()
; #define PG8_SCHED __builtin_amdgcn_sched_barrier(0)
; template <class Epi, class Sched, bool ALIGN_EPI = false, bool SP2 = false>
; __device__ __forceinline__ void gemm_phase(PG8_LAS unsigned char* lds, const Gemm g, const Sched& S, const Epi& E) {
;     ...
;             PG8_WAIT_V(8); PG8_WAIT_L(0); PG8_BAR; PG8_MMA(1, 0, At, B0); PG8_MMA(1, 1, At, B1); PG8_BAR; PG8_SCHED;
;             PG8_LDB(B0, 1, 0); PG8_LDB(B1, 1, 1); PG8_SCHED; PG8_LDA(At, 1, 0); PG8_STAGE(PG8_SA(0, 1), a2 + hstep, voffA);
;             PG8_WAIT_V(8); PG8_WAIT_L(0); PG8_BAR; PG8_MMA(0, 0, At, B0); PG8_MMA(0, 1, At, B1); PG8_BAR; PG8_SCHED;
;             PG8_LDA(At, 1, 1); PG8_STAGE(PG8_SB(1, 0), b3, voffB); PG8_STAGE(PG8_SB(1, 1), b3 + hstep, voffB); PG8_STAGE(PG8_SA(1, 0), a3, voffA);
	s_setprio 1
	s_waitcnt lgkmcnt(0)
	v_mfma_f32_16x16x32_bf16 v[60:63], v[128:131], v[160:163], v[60:63]
	v_mfma_f32_16x16x32_bf16 v[60:63], v[132:135], v[164:167], v[60:63]
	v_mfma_f32_16x16x32_bf16 v[56:59], v[140:143], v[164:167], v[56:59]
	v_mfma_f32_16x16x32_bf16 v[56:59], v[136:139], v[160:163], v[56:59]
	v_mfma_f32_16x16x32_bf16 v[40:43], v[136:139], v[168:171], v[40:43]
	v_mfma_f32_16x16x32_bf16 v[40:43], v[140:143], v[172:175], v[40:43]
	v_mfma_f32_16x16x32_bf16 v[44:47], v[132:135], v[172:175], v[44:47]
	v_mfma_f32_16x16x32_bf16 v[44:47], v[128:131], v[168:171], v[44:47]
	v_mfma_f32_16x16x32_bf16 v[28:31], v[128:131], v[194:197], v[28:31]
	v_mfma_f32_16x16x32_bf16 v[28:31], v[132:135], v[198:201], v[28:31]
	v_mfma_f32_16x16x32_bf16 v[24:27], v[140:143], v[198:201], v[24:27]
	v_mfma_f32_16x16x32_bf16 v[24:27], v[136:139], v[194:197], v[24:27]
	v_mfma_f32_16x16x32_bf16 v[8:11], v[136:139], v[202:205], v[8:11]
	v_mfma_f32_16x16x32_bf16 v[8:11], v[140:143], v[218:221], v[8:11]
	v_mfma_f32_16x16x32_bf16 v[12:15], v[132:135], v[218:221], v[12:15]
	v_mfma_f32_16x16x32_bf16 v[12:15], v[128:131], v[202:205], v[12:15]
	s_setprio 0
	s_setprio 1
	v_mfma_f32_16x16x32_bf16 v[52:55], v[144:147], v[160:163], v[52:55]
	v_mfma_f32_16x16x32_bf16 v[52:55], v[148:151], v[164:167], v[52:55]
	v_mfma_f32_16x16x32_bf16 v[48:51], v[156:159], v[164:167], v[48:51]
	v_mfma_f32_16x16x32_bf16 v[48:51], v[152:155], v[160:163], v[48:51]
	v_mfma_f32_16x16x32_bf16 v[32:35], v[152:155], v[168:171], v[32:35]
	v_mfma_f32_16x16x32_bf16 v[32:35], v[156:159], v[172:175], v[32:35]
	v_mfma_f32_16x16x32_bf16 v[36:39], v[148:151], v[172:175], v[36:39]
	v_mfma_f32_16x16x32_bf16 v[36:39], v[144:147], v[168:171], v[36:39]
	v_mfma_f32_16x16x32_bf16 v[20:23], v[144:147], v[194:197], v[20:23]
	v_mfma_f32_16x16x32_bf16 v[20:23], v[148:151], v[198:201], v[20:23]
	v_mfma_f32_16x16x32_bf16 v[16:19], v[156:159], v[198:201], v[16:19]
	v_mfma_f32_16x16x32_bf16 v[16:19], v[152:155], v[194:197], v[16:19]
	v_mfma_f32_16x16x32_bf16 v[0:3], v[152:155], v[202:205], v[0:3]
	v_mfma_f32_16x16x32_bf16 v[0:3], v[156:159], v[218:221], v[0:3]
	v_mfma_f32_16x16x32_bf16 v[4:7], v[148:151], v[218:221], v[4:7]
	v_mfma_f32_16x16x32_bf16 v[4:7], v[144:147], v[202:205], v[4:7]
	s_setprio 0
	s_barrier
	s_add_i32 s48, 0, 0x18000
	s_add_i32 s49, 0, 0x1c000
	v_add_u32_e32 v140, s48, v207
	v_add_u32_e32 v156, s49, v207
	ds_read_b128 v[128:131], v140
	ds_read_b128 v[132:135], v140 offset:1024
	ds_read_b128 v[136:139], v140 offset:2048
	ds_read_b128 v[140:143], v140 offset:3072
	ds_read_b128 v[144:147], v156
	ds_read_b128 v[148:151], v156 offset:1024
	ds_read_b128 v[152:155], v156 offset:2048
	ds_read_b128 v[156:159], v156 offset:3072
	s_add_u32 s30, s30, 0x80000
	s_addc_u32 s31, s31, 0
	s_mov_b32 m0, s34
	v_lshl_add_u64 v[230:231], s[30:31], 0, v[176:177]
	ds_read_b128 v[160:163], v215 offset:32768
	ds_read_b128 v[164:167], v215 offset:33792
	ds_read_b128 v[168:171], v215 offset:34816
	ds_read_b128 v[172:175], v215 offset:35840
	ds_read_b128 v[194:197], v215 offset:36864
	ds_read_b128 v[198:201], v215 offset:37888
	ds_read_b128 v[202:205], v215 offset:38912
	ds_read_b128 v[218:221], v215 offset:39936
	global_load_lds_dwordx4 v[230:231], off
	v_lshl_add_u64 v[230:231], s[30:31], 0, v[180:181]
	s_mov_b32 m0, s35
	s_nop 0
	global_load_lds_dwordx4 v[230:231], off
	s_waitcnt vmcnt(8)
	s_waitcnt lgkmcnt(0)
	s_barrier
	s_setprio 1
	s_waitcnt lgkmcnt(0)
	v_mfma_f32_16x16x32_bf16 v[124:127], v[128:131], v[160:163], v[124:127]
	v_mfma_f32_16x16x32_bf16 v[124:127], v[132:135], v[164:167], v[124:127]
	v_mfma_f32_16x16x32_bf16 v[120:123], v[140:143], v[164:167], v[120:123]
	v_mfma_f32_16x16x32_bf16 v[120:123], v[136:139], v[160:163], v[120:123]
	v_mfma_f32_16x16x32_bf16 v[104:107], v[136:139], v[168:171], v[104:107]
	v_mfma_f32_16x16x32_bf16 v[104:107], v[140:143], v[172:175], v[104:107]
	v_mfma_f32_16x16x32_bf16 v[108:111], v[132:135], v[172:175], v[108:111]
	v_mfma_f32_16x16x32_bf16 v[108:111], v[128:131], v[168:171], v[108:111]
	v_mfma_f32_16x16x32_bf16 v[92:95], v[128:131], v[194:197], v[92:95]
	v_mfma_f32_16x16x32_bf16 v[92:95], v[132:135], v[198:201], v[92:95]
	v_mfma_f32_16x16x32_bf16 v[88:91], v[140:143], v[198:201], v[88:91]
	v_mfma_f32_16x16x32_bf16 v[88:91], v[136:139], v[194:197], v[88:91]
	v_mfma_f32_16x16x32_bf16 v[72:75], v[136:139], v[202:205], v[72:75]
	v_mfma_f32_16x16x32_bf16 v[72:75], v[140:143], v[218:221], v[72:75]
	v_mfma_f32_16x16x32_bf16 v[76:79], v[132:135], v[218:221], v[76:79]
	v_mfma_f32_16x16x32_bf16 v[76:79], v[128:131], v[202:205], v[76:79]
	s_setprio 0
	s_setprio 1
	v_mfma_f32_16x16x32_bf16 v[116:119], v[144:147], v[160:163], v[116:119]
	v_mfma_f32_16x16x32_bf16 v[116:119], v[148:151], v[164:167], v[116:119]
	v_mfma_f32_16x16x32_bf16 v[112:115], v[156:159], v[164:167], v[112:115]
	v_mfma_f32_16x16x32_bf16 v[112:115], v[152:155], v[160:163], v[112:115]
	v_mfma_f32_16x16x32_bf16 v[96:99], v[152:155], v[168:171], v[96:99]
	v_mfma_f32_16x16x32_bf16 v[96:99], v[156:159], v[172:175], v[96:99]
	v_mfma_f32_16x16x32_bf16 v[100:103], v[148:151], v[172:175], v[100:103]
	v_mfma_f32_16x16x32_bf16 v[100:103], v[144:147], v[168:171], v[100:103]
	v_mfma_f32_16x16x32_bf16 v[84:87], v[144:147], v[194:197], v[84:87]
	v_mfma_f32_16x16x32_bf16 v[84:87], v[148:151], v[198:201], v[84:87]
	v_mfma_f32_16x16x32_bf16 v[80:83], v[156:159], v[198:201], v[80:83]
	v_mfma_f32_16x16x32_bf16 v[80:83], v[152:155], v[194:197], v[80:83]
	v_mfma_f32_16x16x32_bf16 v[64:67], v[152:155], v[202:205], v[64:67]
	v_mfma_f32_16x16x32_bf16 v[64:67], v[156:159], v[218:221], v[64:67]
	v_mfma_f32_16x16x32_bf16 v[68:71], v[148:151], v[218:221], v[68:71]
	v_mfma_f32_16x16x32_bf16 v[68:71], v[144:147], v[202:205], v[68:71]
	s_setprio 0
	s_barrier
; #define PG8_STAGE(bufoff, gbase, voff) do { _Pragma("unroll") for (int _i = 0; _i < 2; ++_i) \
;         __builtin_amdgcn_global_load_lds((const unsigned*)((const char*)(gbase) + (voff)[_i]), (PG8_LAS unsigned*)(lds + (bufoff) + ldsw + _i * 8192), 16, 0, 0); } while (0)
; #define PG8_LDA(dst, b, h) do { _Pragma("unroll") for (int m = 0; m < 4; ++m) _Pragma("unroll") for (int k = 0; k < 2; ++k) dst[m][k] = *(const PG8_LAS bf16x8*)(lds + PG8_SA(b, h) + aoff + m * 2048 + k * 1024); } while (0)
; #define PG8_MMA(ai, bj, At, Bt) do { __builtin_amdgcn_s_setprio(1); _Pragma("unroll") for (int m = 0; m < 4; ++m) _Pragma("unroll") for (int n = 0; n < 2; ++n) _Pragma("unroll") for (int k = 0; k < 2; ++k) \
;         acc[ai][bj][m][n] = __builtin_amdgcn_mfma_f32_16x16x32_bf16(Bt[n][k], At[m][k], acc[ai][bj][m][n], 0, 0, 0); __builtin_amdgcn_s_setprio(0); } while (0)
; #define PG8_WAIT_V(n) asm volatile("s_waitcnt vmcnt(" #n ")" ::: "memory")
; #define PG8_WAIT_L(n) asm volatile("s_waitcnt lgkmcnt(" #n ")" ::: "memory")
; #define PG8_BAR __builtin_amdgcn_s_barrier()
; #define PG8_SCHED __builtin_amdgcn_sched_barrier(0)
; template <class Epi, class Sched, bool ALIGN_EPI = false, bool SP2 = false>
; __device__ __forceinline__ void gemm_phase(PG8_LAS unsigned char* lds, const Gemm g, const Sched& S, const Epi& E) {
;     ...
;         for (int t = 0; t < nt; t += 2) {
;             const bool last = (t == nt - 2);
;             const char* a1 = cA + (size_t)(t + 1) * kstep;
;             const char* a2 = last ? nA : cA + (size_t)(t + 2) * kstep; const char* b2 = last ? nB : cB + (size_t)(t + 2) * kstep;
;             const char* a3 = a2 + kstep; const char* b3 = b2 + kstep;
;     ...
;             PG8_LDA(At, 1, 1); PG8_STAGE(PG8_SB(1, 0), b3, voffB); PG8_STAGE(PG8_SB(1, 1), b3 + hstep, voffB); PG8_STAGE(PG8_SA(1, 0), a3, voffA);
;             PG8_WAIT_V(8); PG8_WAIT_L(0); PG8_BAR; PG8_MMA(1, 0, At, B0); PG8_MMA(1, 1, At, B1); PG8_BAR; PG8_SCHED;
	s_add_i32 s30, s48, s3
	v_lshl_add_u64 v[222:223], v[222:223], 0, s[10:11]
	s_mov_b32 m0, s30
	ds_read_b128 v[160:163], v215 offset:49152
	ds_read_b128 v[164:167], v215 offset:50176
	ds_read_b128 v[168:171], v215 offset:51200
	ds_read_b128 v[172:175], v215 offset:52224
	ds_read_b128 v[194:197], v215 offset:53248
	ds_read_b128 v[198:201], v215 offset:54272
	ds_read_b128 v[202:205], v215 offset:55296
	ds_read_b128 v[218:221], v215 offset:56320
	global_load_lds_dwordx4 v[222:223], off
	s_add_i32 m0, s30, 0x2000
	s_add_u32 s28, s28, 0x80080
	v_lshl_add_u64 v[222:223], v[224:225], 0, s[10:11]
	s_addc_u32 s29, s29, 0
	s_add_i32 s30, s49, s3
	global_load_lds_dwordx4 v[222:223], off
	v_lshl_add_u64 v[222:223], s[28:29], 0, v[178:179]
	s_mov_b32 m0, s30
	s_nop 0
	global_load_lds_dwordx4 v[222:223], off
	v_lshl_add_u64 v[222:223], s[28:29], 0, v[182:183]
	s_add_i32 m0, s30, 0x2000
	s_nop 0
	global_load_lds_dwordx4 v[222:223], off
	v_lshl_add_u64 v[222:223], v[226:227], 0, s[10:11]
	s_mov_b32 m0, s37
	s_nop 0
	global_load_lds_dwordx4 v[222:223], off
	v_lshl_add_u64 v[222:223], v[228:229], 0, s[10:11]
	s_mov_b32 m0, s38
	s_nop 0
	global_load_lds_dwordx4 v[222:223], off
	s_waitcnt vmcnt(8)
	s_waitcnt lgkmcnt(0)
	s_barrier
	s_setprio 1
	s_waitcnt lgkmcnt(0)
	v_mfma_f32_16x16x32_bf16 v[60:63], v[128:131], v[160:163], v[60:63]
	v_mfma_f32_16x16x32_bf16 v[60:63], v[132:135], v[164:167], v[60:63]
	v_mfma_f32_16x16x32_bf16 v[56:59], v[140:143], v[164:167], v[56:59]
	v_mfma_f32_16x16x32_bf16 v[56:59], v[136:139], v[160:163], v[56:59]
	v_mfma_f32_16x16x32_bf16 v[40:43], v[136:139], v[168:171], v[40:43]
	v_mfma_f32_16x16x32_bf16 v[40:43], v[140:143], v[172:175], v[40:43]
	v_mfma_f32_16x16x32_bf16 v[44:47], v[132:135], v[172:175], v[44:47]
	v_mfma_f32_16x16x32_bf16 v[44:47], v[128:131], v[168:171], v[44:47]
	v_mfma_f32_16x16x32_bf16 v[28:31], v[128:131], v[194:197], v[28:31]
	v_mfma_f32_16x16x32_bf16 v[28:31], v[132:135], v[198:201], v[28:31]
	v_mfma_f32_16x16x32_bf16 v[24:27], v[140:143], v[198:201], v[24:27]
	v_mfma_f32_16x16x32_bf16 v[24:27], v[136:139], v[194:197], v[24:27]
	v_mfma_f32_16x16x32_bf16 v[8:11], v[136:139], v[202:205], v[8:11]
	v_mfma_f32_16x16x32_bf16 v[8:11], v[140:143], v[218:221], v[8:11]
	v_mfma_f32_16x16x32_bf16 v[12:15], v[132:135], v[218:221], v[12:15]
	v_mfma_f32_16x16x32_bf16 v[12:15], v[128:131], v[202:205], v[12:15]
	s_setprio 0
	s_setprio 1
	v_mfma_f32_16x16x32_bf16 v[52:55], v[144:147], v[160:163], v[52:55]
	v_mfma_f32_16x16x32_bf16 v[52:55], v[148:151], v[164:167], v[52:55]
	v_mfma_f32_16x16x32_bf16 v[48:51], v[156:159], v[164:167], v[48:51]
	v_mfma_f32_16x16x32_bf16 v[48:51], v[152:155], v[160:163], v[48:51]
	v_mfma_f32_16x16x32_bf16 v[32:35], v[152:155], v[168:171], v[32:35]
	v_mfma_f32_16x16x32_bf16 v[32:35], v[156:159], v[172:175], v[32:35]
	v_mfma_f32_16x16x32_bf16 v[36:39], v[148:151], v[172:175], v[36:39]
	v_mfma_f32_16x16x32_bf16 v[36:39], v[144:147], v[168:171], v[36:39]
	v_mfma_f32_16x16x32_bf16 v[20:23], v[144:147], v[194:197], v[20:23]
	v_mfma_f32_16x16x32_bf16 v[20:23], v[148:151], v[198:201], v[20:23]
	v_mfma_f32_16x16x32_bf16 v[16:19], v[156:159], v[198:201], v[16:19]
	v_mfma_f32_16x16x32_bf16 v[16:19], v[152:155], v[194:197], v[16:19]
	v_mfma_f32_16x16x32_bf16 v[0:3], v[152:155], v[202:205], v[0:3]
	v_mfma_f32_16x16x32_bf16 v[0:3], v[156:159], v[218:221], v[0:3]
	v_mfma_f32_16x16x32_bf16 v[4:7], v[148:151], v[218:221], v[4:7]
	v_mfma_f32_16x16x32_bf16 v[4:7], v[144:147], v[202:205], v[4:7]
	s_setprio 0
	s_barrier
	s_add_i32 s47, s47, 2
	s_add_u32 s26, s26, 0x100
	s_addc_u32 s27, s27, 0
	s_add_u32 s45, s45, 0x100
	s_addc_u32 s46, s46, 0
	s_cmp_gt_u32 s47, 29
	s_cbranch_scc0 .LBB0_692
	s_and_b64 vcc, exec, s[12:13]
	s_cbranch_vccz .LBB0_695
	s_barrier

; #define PG8_STAGE(bufoff, gbase, voff) do { _Pragma("unroll") for (int _i = 0; _i < 2; ++_i) \
;         __builtin_amdgcn_global_load_lds((const unsigned*)((const char*)(gbase) + (voff)[_i]), (PG8_LAS unsigned*)(lds + (bufoff) + ldsw + _i * 8192), 16, 0, 0); } while (0)
; #define PG8_LDA(dst, b, h) do { _Pragma("unroll") for (int m = 0; m < 4; ++m) _Pragma("unroll") for (int k = 0; k < 2; ++k) dst[m][k] = *(const PG8_LAS bf16x8*)(lds + PG8_SA(b, h) + aoff + m * 2048 + k * 1024); } while (0)
; #define PG8_LDB(dst, b, h) do { _Pragma("unroll") for (int n = 0; n < 2; ++n) _Pragma("unroll") for (int k = 0; k < 2; ++k) dst[n][k] = *(const PG8_LAS bf16x8*)(lds + PG8_SB(b, h) + boff + n * 2048 + k * 1024); } while (0)
; #define PG8_MMA(ai, bj, At, Bt) do { __builtin_amdgcn_s_setprio(1); _Pragma("unroll") for (int m = 0; m < 4; ++m) _Pragma("unroll") for (int n = 0; n < 2; ++n) _Pragma("unroll") for (int k = 0; k < 2; ++k) \
;         acc[ai][bj][m][n] = __builtin_amdgcn_mfma_f32_16x16x32_bf16(Bt[n][k], At[m][k], acc[ai][bj][m][n], 0, 0, 0); __builtin_amdgcn_s_setprio(0); } while (0)
; #define PG8_WAIT_V(n) asm volatile("s_waitcnt vmcnt(" #n ")" ::: "memory")
; template <class Epi, class Sched, bool ALIGN_EPI = false, bool SP2 = false>
; __device__ __forceinline__ void gemm_phase(PG8_LAS unsigned char* lds, const Gemm g, const Sched& S, const Epi& E) {
;     ...
;             PG8_LDB(B0, 0, 0); PG8_LDB(B1, 0, 1); PG8_SCHED; PG8_LDA(At, 0, 0); PG8_STAGE(PG8_SA(1, 1), a1 + hstep, voffA);
;             PG8_WAIT_V(8); PG8_WAIT_L(0); PG8_BAR; PG8_MMA(0, 0, At, B0); PG8_MMA(0, 1, At, B1); PG8_BAR; PG8_SCHED;
;             PG8_LDA(At, 0, 1); PG8_STAGE(PG8_SB(0, 0), b2, voffB); PG8_STAGE(PG8_SB(0, 1), b2 + hstep, voffB); PG8_STAGE(PG8_SA(0, 0), a2, voffA);
;             PG8_WAIT_V(8); PG8_WAIT_L(0); PG8_BAR; PG8_MMA(1, 0, At, B0); PG8_MMA(1, 1, At, B1); PG8_BAR; PG8_SCHED;
;             PG8_LDB(B0, 1, 0); PG8_LDB(B1, 1, 1); PG8_SCHED; PG8_LDA(At, 1, 0); PG8_STAGE(PG8_SA(0, 1), a2 + hstep, voffA);
;             PG8_WAIT_V(8); PG8_WAIT_L(0); PG8_BAR; PG8_MMA(0, 0, At, B0); PG8_MMA(0, 1, At, B1); PG8_BAR; PG8_SCHED;
;             PG8_LDA(At, 1, 1); PG8_STAGE(PG8_SB(1, 0), b3, voffB); PG8_STAGE(PG8_SB(1, 1), b3 + hstep, voffB); PG8_STAGE(PG8_SA(1, 0), a3, voffA);
;             PG8_WAIT_V(8); PG8_WAIT_L(0); PG8_BAR; PG8_MMA(1, 0, At, B0); PG8_MMA(1, 1, At, B1); PG8_BAR; PG8_SCHED;
.Lp5_kloop0:
	s_waitcnt vmcnt(8)
	s_waitcnt lgkmcnt(0)
	s_barrier
	v_mfma_f32_16x16x32_bf16 v[0:3], v[194:197], v[128:131], v[0:3]
	ds_read_b128 v[210:213], v247 offset:16384
	v_mfma_f32_16x16x32_bf16 v[0:3], v[198:201], v[132:135], v[0:3]
	ds_read_b128 v[214:217], v248 offset:16384
	v_mfma_f32_16x16x32_bf16 v[4:7], v[206:209], v[132:135], v[4:7]
	ds_read_b128 v[218:221], v247 offset:18432
	v_mfma_f32_16x16x32_bf16 v[4:7], v[202:205], v[128:131], v[4:7]
	ds_read_b128 v[222:225], v248 offset:18432
	v_mfma_f32_16x16x32_bf16 v[12:15], v[202:205], v[136:139], v[12:15]
	s_add_i32 m0, s35, 0x0
	v_mfma_f32_16x16x32_bf16 v[12:15], v[206:209], v[140:143], v[12:15]
	global_load_lds_dwordx4 v249, s[30:31]
	v_mfma_f32_16x16x32_bf16 v[8:11], v[198:201], v[140:143], v[8:11]
	s_add_i32 m0, s35, 0x2000
	v_mfma_f32_16x16x32_bf16 v[8:11], v[194:197], v[136:139], v[8:11]
	global_load_lds_dwordx4 v250, s[30:31]
	v_mfma_f32_16x16x32_bf16 v[16:19], v[194:197], v[144:147], v[16:19]
	s_add_i32 m0, s35, 0x10000
	v_mfma_f32_16x16x32_bf16 v[16:19], v[198:201], v[148:151], v[16:19]
	global_load_lds_dwordx4 v251, s[32:33]
	v_mfma_f32_16x16x32_bf16 v[20:23], v[206:209], v[148:151], v[20:23]
	s_add_i32 m0, s35, 0x12000
	v_mfma_f32_16x16x32_bf16 v[20:23], v[202:205], v[144:147], v[20:23]
	global_load_lds_dwordx4 v252, s[32:33]
	v_mfma_f32_16x16x32_bf16 v[28:31], v[202:205], v[152:155], v[28:31]
	ds_read_b128 v[160:163], v245 offset:16384
	v_mfma_f32_16x16x32_bf16 v[28:31], v[206:209], v[156:159], v[28:31]
	ds_read_b128 v[164:167], v246 offset:16384
	v_mfma_f32_16x16x32_bf16 v[24:27], v[198:201], v[156:159], v[24:27]
	ds_read_b128 v[168:171], v245 offset:18432
	v_mfma_f32_16x16x32_bf16 v[24:27], v[194:197], v[152:155], v[24:27]
	ds_read_b128 v[172:175], v246 offset:18432
	s_waitcnt lgkmcnt(4)
	v_mfma_f32_16x16x32_bf16 v[32:35], v[210:213], v[128:131], v[32:35]
	ds_read_b128 v[176:179], v245 offset:20480
	v_mfma_f32_16x16x32_bf16 v[32:35], v[214:217], v[132:135], v[32:35]
	ds_read_b128 v[180:183], v246 offset:20480
	v_mfma_f32_16x16x32_bf16 v[36:39], v[222:225], v[132:135], v[36:39]
	ds_read_b128 v[186:189], v245 offset:22528
	v_mfma_f32_16x16x32_bf16 v[36:39], v[218:221], v[128:131], v[36:39]
	ds_read_b128 v[190:193], v246 offset:22528
	v_mfma_f32_16x16x32_bf16 v[44:47], v[218:221], v[136:139], v[44:47]
	v_mfma_f32_16x16x32_bf16 v[44:47], v[222:225], v[140:143], v[44:47]
	v_mfma_f32_16x16x32_bf16 v[40:43], v[214:217], v[140:143], v[40:43]
	v_mfma_f32_16x16x32_bf16 v[40:43], v[210:213], v[136:139], v[40:43]
	v_mfma_f32_16x16x32_bf16 v[48:51], v[210:213], v[144:147], v[48:51]
	v_mfma_f32_16x16x32_bf16 v[48:51], v[214:217], v[148:151], v[48:51]
	v_mfma_f32_16x16x32_bf16 v[52:55], v[222:225], v[148:151], v[52:55]
	v_mfma_f32_16x16x32_bf16 v[52:55], v[218:221], v[144:147], v[52:55]
	v_mfma_f32_16x16x32_bf16 v[60:63], v[218:221], v[152:155], v[60:63]
	v_mfma_f32_16x16x32_bf16 v[60:63], v[222:225], v[156:159], v[60:63]
	v_mfma_f32_16x16x32_bf16 v[56:59], v[214:217], v[156:159], v[56:59]
	v_mfma_f32_16x16x32_bf16 v[56:59], v[210:213], v[152:155], v[56:59]
	s_waitcnt vmcnt(8)
	s_waitcnt lgkmcnt(0)
	s_barrier
	v_mfma_f32_16x16x32_bf16 v[96:99], v[210:213], v[160:163], v[96:99]
	s_add_i32 m0, s35, 0x4000
	v_mfma_f32_16x16x32_bf16 v[96:99], v[214:217], v[164:167], v[96:99]
	global_load_lds_dwordx4 v249, s[56:57]
	v_mfma_f32_16x16x32_bf16 v[100:103], v[222:225], v[164:167], v[100:103]
	s_add_i32 m0, s35, 0x6000
	v_mfma_f32_16x16x32_bf16 v[100:103], v[218:221], v[160:163], v[100:103]
	global_load_lds_dwordx4 v250, s[56:57]
	v_mfma_f32_16x16x32_bf16 v[108:111], v[218:221], v[168:171], v[108:111]
	s_add_i32 m0, s35, 0x14000
	v_mfma_f32_16x16x32_bf16 v[108:111], v[222:225], v[172:175], v[108:111]
	global_load_lds_dwordx4 v251, s[58:59]
	v_mfma_f32_16x16x32_bf16 v[104:107], v[214:217], v[172:175], v[104:107]
	s_add_i32 m0, s35, 0x16000
	v_mfma_f32_16x16x32_bf16 v[104:107], v[210:213], v[168:171], v[104:107]
	global_load_lds_dwordx4 v252, s[58:59]
	v_mfma_f32_16x16x32_bf16 v[112:115], v[210:213], v[176:179], v[112:115]
	ds_read_b128 v[128:131], v245 offset:32768
	v_mfma_f32_16x16x32_bf16 v[112:115], v[214:217], v[180:183], v[112:115]
	ds_read_b128 v[132:135], v246 offset:32768
	v_mfma_f32_16x16x32_bf16 v[116:119], v[222:225], v[180:183], v[116:119]
	ds_read_b128 v[136:139], v245 offset:34816
	v_mfma_f32_16x16x32_bf16 v[116:119], v[218:221], v[176:179], v[116:119]
	ds_read_b128 v[140:143], v246 offset:34816
	v_mfma_f32_16x16x32_bf16 v[124:127], v[218:221], v[186:189], v[124:127]
	ds_read_b128 v[144:147], v245 offset:36864
	v_mfma_f32_16x16x32_bf16 v[124:127], v[222:225], v[190:193], v[124:127]
	ds_read_b128 v[148:151], v246 offset:36864
	v_mfma_f32_16x16x32_bf16 v[120:123], v[214:217], v[190:193], v[120:123]
	ds_read_b128 v[152:155], v245 offset:38912
	v_mfma_f32_16x16x32_bf16 v[120:123], v[210:213], v[186:189], v[120:123]
	ds_read_b128 v[156:159], v246 offset:38912
	v_mfma_f32_16x16x32_bf16 v[64:67], v[194:197], v[160:163], v[64:67]
	ds_read_b128 v[210:213], v247 offset:49152
	v_mfma_f32_16x16x32_bf16 v[64:67], v[198:201], v[164:167], v[64:67]
	ds_read_b128 v[214:217], v248 offset:49152
	v_mfma_f32_16x16x32_bf16 v[68:71], v[206:209], v[164:167], v[68:71]
	ds_read_b128 v[218:221], v247 offset:51200
	v_mfma_f32_16x16x32_bf16 v[68:71], v[202:205], v[160:163], v[68:71]
	ds_read_b128 v[222:225], v248 offset:51200
	v_mfma_f32_16x16x32_bf16 v[76:79], v[202:205], v[168:171], v[76:79]
	s_add_u32 s30, s30, s4
	s_addc_u32 s31, s31, s5
	v_mfma_f32_16x16x32_bf16 v[76:79], v[206:209], v[172:175], v[76:79]
	s_add_u32 s56, s56, s4
	s_addc_u32 s57, s57, s5
	v_mfma_f32_16x16x32_bf16 v[72:75], v[198:201], v[172:175], v[72:75]
	s_add_u32 s32, s32, s4
	s_addc_u32 s33, s33, s5
	v_mfma_f32_16x16x32_bf16 v[72:75], v[194:197], v[168:171], v[72:75]
	s_add_u32 s58, s58, s4
	s_addc_u32 s59, s59, s5
	v_mfma_f32_16x16x32_bf16 v[80:83], v[194:197], v[176:179], v[80:83]
	v_mfma_f32_16x16x32_bf16 v[80:83], v[198:201], v[180:183], v[80:83]
	v_mfma_f32_16x16x32_bf16 v[84:87], v[206:209], v[180:183], v[84:87]
	v_mfma_f32_16x16x32_bf16 v[84:87], v[202:205], v[176:179], v[84:87]
	v_mfma_f32_16x16x32_bf16 v[92:95], v[202:205], v[186:189], v[92:95]
	v_mfma_f32_16x16x32_bf16 v[92:95], v[206:209], v[190:193], v[92:95]
	v_mfma_f32_16x16x32_bf16 v[88:91], v[198:201], v[190:193], v[88:91]
	v_mfma_f32_16x16x32_bf16 v[88:91], v[194:197], v[186:189], v[88:91]
	s_waitcnt vmcnt(8)
	s_waitcnt lgkmcnt(0)
	s_barrier
; #define PG8_STAGE(bufoff, gbase, voff) do { _Pragma("unroll") for (int _i = 0; _i < 2; ++_i) \
;         __builtin_amdgcn_global_load_lds((const unsigned*)((const char*)(gbase) + (voff)[_i]), (PG8_LAS unsigned*)(lds + (bufoff) + ldsw + _i * 8192), 16, 0, 0); } while (0)
; #define PG8_LDA(dst, b, h) do { _Pragma("unroll") for (int m = 0; m < 4; ++m) _Pragma("unroll") for (int k = 0; k < 2; ++k) dst[m][k] = *(const PG8_LAS bf16x8*)(lds + PG8_SA(b, h) + aoff + m * 2048 + k * 1024); } while (0)
; #define PG8_WAIT_V(n) asm volatile("s_waitcnt vmcnt(" #n ")" ::: "memory")
; template <class Epi, class Sched, bool ALIGN_EPI = false, bool SP2 = false>
; __device__ __forceinline__ void gemm_phase(PG8_LAS unsigned char* lds, const Gemm g, const Sched& S, const Epi& E) {
;     ...
;         const bool has_next = S.next(ui + 1, nxt);
;         const char* nA = has_next ? (const char*)g.A + (size_t)nxt.pm * tstep : cA; const char* nB = has_next ? (const char*)g.Bt + (size_t)nxt.pn * tstep : cB;
;         for (int t = 0; t < nt; t += 2) {
;             const bool last = (t == nt - 2);
;             const char* a1 = cA + (size_t)(t + 1) * kstep;
;             const char* a2 = last ? nA : cA + (size_t)(t + 2) * kstep; const char* b2 = last ? nB : cB + (size_t)(t + 2) * kstep;
;             const char* a3 = a2 + kstep; const char* b3 = b2 + kstep;
;     ...
;             PG8_LDB(B0, 0, 0); PG8_LDB(B1, 0, 1); PG8_SCHED; PG8_LDA(At, 0, 0); PG8_STAGE(PG8_SA(1, 1), a1 + hstep, voffA);
;             PG8_WAIT_V(8); PG8_WAIT_L(0); PG8_BAR; PG8_MMA(0, 0, At, B0); PG8_MMA(0, 1, At, B1); PG8_BAR; PG8_SCHED;
;             PG8_LDA(At, 0, 1); PG8_STAGE(PG8_SB(0, 0), b2, voffB); PG8_STAGE(PG8_SB(0, 1), b2 + hstep, voffB); PG8_STAGE(PG8_SA(0, 0), a2, voffA);
;             PG8_WAIT_V(8); PG8_WAIT_L(0); PG8_BAR; PG8_MMA(1, 0, At, B0); PG8_MMA(1, 1, At, B1); PG8_BAR; PG8_SCHED;
;             PG8_LDB(B0, 1, 0); PG8_LDB(B1, 1, 1); PG8_SCHED; PG8_LDA(At, 1, 0); PG8_STAGE(PG8_SA(0, 1), a2 + hstep, voffA);
;             PG8_WAIT_V(8); PG8_WAIT_L(0); PG8_BAR; PG8_MMA(0, 0, At, B0); PG8_MMA(0, 1, At, B1); PG8_BAR; PG8_SCHED;
;             PG8_LDA(At, 1, 1); PG8_STAGE(PG8_SB(1, 0), b3, voffB); PG8_STAGE(PG8_SB(1, 1), b3 + hstep, voffB); PG8_STAGE(PG8_SA(1, 0), a3, voffA);
;             PG8_WAIT_V(8); PG8_WAIT_L(0); PG8_BAR; PG8_MMA(1, 0, At, B0); PG8_MMA(1, 1, At, B1); PG8_BAR; PG8_SCHED;
	v_mfma_f32_16x16x32_bf16 v[32:35], v[210:213], v[128:131], v[32:35]
	ds_read_b128 v[194:197], v247 offset:32768
	v_mfma_f32_16x16x32_bf16 v[32:35], v[214:217], v[132:135], v[32:35]
	ds_read_b128 v[198:201], v248 offset:32768
	v_mfma_f32_16x16x32_bf16 v[36:39], v[222:225], v[132:135], v[36:39]
	ds_read_b128 v[202:205], v247 offset:34816
	v_mfma_f32_16x16x32_bf16 v[36:39], v[218:221], v[128:131], v[36:39]
	ds_read_b128 v[206:209], v248 offset:34816
	v_mfma_f32_16x16x32_bf16 v[44:47], v[218:221], v[136:139], v[44:47]
	s_add_i32 m0, s35, 0x8000
	v_mfma_f32_16x16x32_bf16 v[44:47], v[222:225], v[140:143], v[44:47]
	global_load_lds_dwordx4 v249, s[30:31]
	v_mfma_f32_16x16x32_bf16 v[40:43], v[214:217], v[140:143], v[40:43]
	s_add_i32 m0, s35, 0xa000
	v_mfma_f32_16x16x32_bf16 v[40:43], v[210:213], v[136:139], v[40:43]
	global_load_lds_dwordx4 v250, s[30:31]
	v_mfma_f32_16x16x32_bf16 v[48:51], v[210:213], v[144:147], v[48:51]
	s_add_i32 m0, s35, 0x1c000
	v_mfma_f32_16x16x32_bf16 v[48:51], v[214:217], v[148:151], v[48:51]
	global_load_lds_dwordx4 v251, s[58:59]
	v_mfma_f32_16x16x32_bf16 v[52:55], v[222:225], v[148:151], v[52:55]
	s_add_i32 m0, s35, 0x1e000
	v_mfma_f32_16x16x32_bf16 v[52:55], v[218:221], v[144:147], v[52:55]
	global_load_lds_dwordx4 v252, s[58:59]
	v_mfma_f32_16x16x32_bf16 v[60:63], v[218:221], v[152:155], v[60:63]
	ds_read_b128 v[160:163], v245 offset:49152
	v_mfma_f32_16x16x32_bf16 v[60:63], v[222:225], v[156:159], v[60:63]
	ds_read_b128 v[164:167], v246 offset:49152
	v_mfma_f32_16x16x32_bf16 v[56:59], v[214:217], v[156:159], v[56:59]
	ds_read_b128 v[168:171], v245 offset:51200
	v_mfma_f32_16x16x32_bf16 v[56:59], v[210:213], v[152:155], v[56:59]
	ds_read_b128 v[172:175], v246 offset:51200
	s_waitcnt lgkmcnt(4)
	v_mfma_f32_16x16x32_bf16 v[0:3], v[194:197], v[128:131], v[0:3]
	ds_read_b128 v[176:179], v245 offset:53248
	v_mfma_f32_16x16x32_bf16 v[0:3], v[198:201], v[132:135], v[0:3]
	ds_read_b128 v[180:183], v246 offset:53248
	v_mfma_f32_16x16x32_bf16 v[4:7], v[206:209], v[132:135], v[4:7]
	ds_read_b128 v[186:189], v245 offset:55296
	v_mfma_f32_16x16x32_bf16 v[4:7], v[202:205], v[128:131], v[4:7]
	ds_read_b128 v[190:193], v246 offset:55296
	v_mfma_f32_16x16x32_bf16 v[12:15], v[202:205], v[136:139], v[12:15]
	v_mfma_f32_16x16x32_bf16 v[12:15], v[206:209], v[140:143], v[12:15]
	v_mfma_f32_16x16x32_bf16 v[8:11], v[198:201], v[140:143], v[8:11]
	v_mfma_f32_16x16x32_bf16 v[8:11], v[194:197], v[136:139], v[8:11]
	v_mfma_f32_16x16x32_bf16 v[16:19], v[194:197], v[144:147], v[16:19]
	v_mfma_f32_16x16x32_bf16 v[16:19], v[198:201], v[148:151], v[16:19]
	v_mfma_f32_16x16x32_bf16 v[20:23], v[206:209], v[148:151], v[20:23]
	v_mfma_f32_16x16x32_bf16 v[20:23], v[202:205], v[144:147], v[20:23]
	v_mfma_f32_16x16x32_bf16 v[28:31], v[202:205], v[152:155], v[28:31]
	v_mfma_f32_16x16x32_bf16 v[28:31], v[206:209], v[156:159], v[28:31]
	v_mfma_f32_16x16x32_bf16 v[24:27], v[198:201], v[156:159], v[24:27]
	v_mfma_f32_16x16x32_bf16 v[24:27], v[194:197], v[152:155], v[24:27]
	s_waitcnt vmcnt(8)
	s_waitcnt lgkmcnt(0)
	s_barrier
	v_mfma_f32_16x16x32_bf16 v[64:67], v[194:197], v[160:163], v[64:67]
	s_add_i32 m0, s35, 0xc000
	v_mfma_f32_16x16x32_bf16 v[64:67], v[198:201], v[164:167], v[64:67]
	global_load_lds_dwordx4 v249, s[56:57]
	v_mfma_f32_16x16x32_bf16 v[68:71], v[206:209], v[164:167], v[68:71]
	s_add_i32 m0, s35, 0xe000
	v_mfma_f32_16x16x32_bf16 v[68:71], v[202:205], v[160:163], v[68:71]
	global_load_lds_dwordx4 v250, s[56:57]
	v_mfma_f32_16x16x32_bf16 v[76:79], v[202:205], v[168:171], v[76:79]
	s_add_i32 m0, s35, 0x18000
	v_mfma_f32_16x16x32_bf16 v[76:79], v[206:209], v[172:175], v[76:79]
	global_load_lds_dwordx4 v251, s[32:33]
	v_mfma_f32_16x16x32_bf16 v[72:75], v[198:201], v[172:175], v[72:75]
	s_add_i32 m0, s35, 0x1a000
	v_mfma_f32_16x16x32_bf16 v[72:75], v[194:197], v[168:171], v[72:75]
	global_load_lds_dwordx4 v252, s[32:33]
	v_mfma_f32_16x16x32_bf16 v[80:83], v[194:197], v[176:179], v[80:83]
	ds_read_b128 v[128:131], v245 offset:0
	v_mfma_f32_16x16x32_bf16 v[80:83], v[198:201], v[180:183], v[80:83]
	ds_read_b128 v[132:135], v246 offset:0
	v_mfma_f32_16x16x32_bf16 v[84:87], v[206:209], v[180:183], v[84:87]
	ds_read_b128 v[136:139], v245 offset:2048
	v_mfma_f32_16x16x32_bf16 v[84:87], v[202:205], v[176:179], v[84:87]
	ds_read_b128 v[140:143], v246 offset:2048
	v_mfma_f32_16x16x32_bf16 v[92:95], v[202:205], v[186:189], v[92:95]
	ds_read_b128 v[144:147], v245 offset:4096
	v_mfma_f32_16x16x32_bf16 v[92:95], v[206:209], v[190:193], v[92:95]
	ds_read_b128 v[148:151], v246 offset:4096
	v_mfma_f32_16x16x32_bf16 v[88:91], v[198:201], v[190:193], v[88:91]
	ds_read_b128 v[152:155], v245 offset:6144
	v_mfma_f32_16x16x32_bf16 v[88:91], v[194:197], v[186:189], v[88:91]
	ds_read_b128 v[156:159], v246 offset:6144
	v_mfma_f32_16x16x32_bf16 v[96:99], v[210:213], v[160:163], v[96:99]
	ds_read_b128 v[194:197], v247 offset:0
	v_mfma_f32_16x16x32_bf16 v[96:99], v[214:217], v[164:167], v[96:99]
	ds_read_b128 v[198:201], v248 offset:0
	v_mfma_f32_16x16x32_bf16 v[100:103], v[222:225], v[164:167], v[100:103]
	ds_read_b128 v[202:205], v247 offset:2048
	v_mfma_f32_16x16x32_bf16 v[100:103], v[218:221], v[160:163], v[100:103]
	ds_read_b128 v[206:209], v248 offset:2048
	v_mfma_f32_16x16x32_bf16 v[108:111], v[218:221], v[168:171], v[108:111]
	s_add_u32 s30, s30, s4
	s_addc_u32 s31, s31, s5
	v_mfma_f32_16x16x32_bf16 v[108:111], v[222:225], v[172:175], v[108:111]
	s_add_u32 s56, s56, s4
	s_addc_u32 s57, s57, s5
	v_mfma_f32_16x16x32_bf16 v[104:107], v[214:217], v[172:175], v[104:107]
	s_add_u32 s32, s32, s4
	s_addc_u32 s33, s33, s5
	v_mfma_f32_16x16x32_bf16 v[104:107], v[210:213], v[168:171], v[104:107]
	s_add_u32 s58, s58, s4
	s_addc_u32 s59, s59, s5
	v_mfma_f32_16x16x32_bf16 v[112:115], v[210:213], v[176:179], v[112:115]
	v_mfma_f32_16x16x32_bf16 v[112:115], v[214:217], v[180:183], v[112:115]
	v_mfma_f32_16x16x32_bf16 v[116:119], v[222:225], v[180:183], v[116:119]
	v_mfma_f32_16x16x32_bf16 v[116:119], v[218:221], v[176:179], v[116:119]
	v_mfma_f32_16x16x32_bf16 v[124:127], v[218:221], v[186:189], v[124:127]
	v_mfma_f32_16x16x32_bf16 v[124:127], v[222:225], v[190:193], v[124:127]
	v_mfma_f32_16x16x32_bf16 v[120:123], v[214:217], v[190:193], v[120:123]
	v_mfma_f32_16x16x32_bf16 v[120:123], v[210:213], v[186:189], v[120:123]
	s_add_i32 s34, s34, -1
	s_cmp_lg_u32 s34, 1
	s_cbranch_scc1 .Lp5_nosw0
	s_add_u32 s45, s16, 1
	s_and_b32 s40, s45, 1
	s_lshl_b32 s4, s40, 8
	s_sub_u32 s4, 128, s4
	s_sub_u32 s5, 0, s40
	s_mul_i32 s8, s40, 3968
	s_add_u32 s30, s26, s8
	s_addc_u32 s31, s27, 0
	s_add_u32 s32, s28, s8
	s_addc_u32 s33, s29, 0
	s_add_u32 s56, s30, 0x80000
	s_addc_u32 s57, s31, 0
	s_add_u32 s58, s32, 0x80000
	s_addc_u32 s59, s33, 0

; #define PG8_STAGE(bufoff, gbase, voff) do { _Pragma("unroll") for (int _i = 0; _i < 2; ++_i) \
;         __builtin_amdgcn_global_load_lds((const unsigned*)((const char*)(gbase) + (voff)[_i]), (PG8_LAS unsigned*)(lds + (bufoff) + ldsw + _i * 8192), 16, 0, 0); } while (0)
; #define PG8_LDA(dst, b, h) do { _Pragma("unroll") for (int m = 0; m < 4; ++m) _Pragma("unroll") for (int k = 0; k < 2; ++k) dst[m][k] = *(const PG8_LAS bf16x8*)(lds + PG8_SA(b, h) + aoff + m * 2048 + k * 1024); } while (0)
; #define PG8_LDB(dst, b, h) do { _Pragma("unroll") for (int n = 0; n < 2; ++n) _Pragma("unroll") for (int k = 0; k < 2; ++k) dst[n][k] = *(const PG8_LAS bf16x8*)(lds + PG8_SB(b, h) + boff + n * 2048 + k * 1024); } while (0)
; #define PG8_MMA(ai, bj, At, Bt) do { __builtin_amdgcn_s_setprio(1); _Pragma("unroll") for (int m = 0; m < 4; ++m) _Pragma("unroll") for (int n = 0; n < 2; ++n) _Pragma("unroll") for (int k = 0; k < 2; ++k) \
;         acc[ai][bj][m][n] = __builtin_amdgcn_mfma_f32_16x16x32_bf16(Bt[n][k], At[m][k], acc[ai][bj][m][n], 0, 0, 0); __builtin_amdgcn_s_setprio(0); } while (0)
; #define PG8_WAIT_V(n) asm volatile("s_waitcnt vmcnt(" #n ")" ::: "memory")
; template <class Epi, class Sched, bool ALIGN_EPI = false, bool SP2 = false>
; __device__ __forceinline__ void gemm_phase(PG8_LAS unsigned char* lds, const Gemm g, const Sched& S, const Epi& E) {
;     ...
;             PG8_LDB(B0, 0, 0); PG8_LDB(B1, 0, 1); PG8_SCHED; PG8_LDA(At, 0, 0); PG8_STAGE(PG8_SA(1, 1), a1 + hstep, voffA);
;             PG8_WAIT_V(8); PG8_WAIT_L(0); PG8_BAR; PG8_MMA(0, 0, At, B0); PG8_MMA(0, 1, At, B1); PG8_BAR; PG8_SCHED;
;             PG8_LDA(At, 0, 1); PG8_STAGE(PG8_SB(0, 0), b2, voffB); PG8_STAGE(PG8_SB(0, 1), b2 + hstep, voffB); PG8_STAGE(PG8_SA(0, 0), a2, voffA);
;             PG8_WAIT_V(8); PG8_WAIT_L(0); PG8_BAR; PG8_MMA(1, 0, At, B0); PG8_MMA(1, 1, At, B1); PG8_BAR; PG8_SCHED;
;             PG8_LDB(B0, 1, 0); PG8_LDB(B1, 1, 1); PG8_SCHED; PG8_LDA(At, 1, 0); PG8_STAGE(PG8_SA(0, 1), a2 + hstep, voffA);
;             PG8_WAIT_V(8); PG8_WAIT_L(0); PG8_BAR; PG8_MMA(0, 0, At, B0); PG8_MMA(0, 1, At, B1); PG8_BAR; PG8_SCHED;
;             PG8_LDA(At, 1, 1); PG8_STAGE(PG8_SB(1, 0), b3, voffB); PG8_STAGE(PG8_SB(1, 1), b3 + hstep, voffB); PG8_STAGE(PG8_SA(1, 0), a3, voffA);
;             PG8_WAIT_V(8); PG8_WAIT_L(0); PG8_BAR; PG8_MMA(1, 0, At, B0); PG8_MMA(1, 1, At, B1); PG8_BAR; PG8_SCHED;
.Lp5_kloop1:
	s_waitcnt vmcnt(8)
	s_waitcnt lgkmcnt(0)
	s_barrier
	v_mfma_f32_16x16x32_bf16 v[0:3], v[194:197], v[128:131], v[0:3]
	ds_read_b128 v[210:213], v247 offset:16384
	v_mfma_f32_16x16x32_bf16 v[0:3], v[198:201], v[132:135], v[0:3]
	ds_read_b128 v[214:217], v248 offset:16384
	v_mfma_f32_16x16x32_bf16 v[4:7], v[206:209], v[132:135], v[4:7]
	ds_read_b128 v[218:221], v247 offset:18432
	v_mfma_f32_16x16x32_bf16 v[4:7], v[202:205], v[128:131], v[4:7]
	ds_read_b128 v[222:225], v248 offset:18432
	v_mfma_f32_16x16x32_bf16 v[12:15], v[202:205], v[136:139], v[12:15]
	ds_read_b128 v[160:163], v245 offset:16384
	v_mfma_f32_16x16x32_bf16 v[12:15], v[206:209], v[140:143], v[12:15]
	ds_read_b128 v[164:167], v246 offset:16384
	v_mfma_f32_16x16x32_bf16 v[8:11], v[198:201], v[140:143], v[8:11]
	ds_read_b128 v[168:171], v245 offset:18432
	v_mfma_f32_16x16x32_bf16 v[8:11], v[194:197], v[136:139], v[8:11]
	ds_read_b128 v[172:175], v246 offset:18432
	v_mfma_f32_16x16x32_bf16 v[16:19], v[194:197], v[144:147], v[16:19]
	ds_read_b128 v[176:179], v245 offset:20480
	v_mfma_f32_16x16x32_bf16 v[16:19], v[198:201], v[148:151], v[16:19]
	ds_read_b128 v[180:183], v246 offset:20480
	v_mfma_f32_16x16x32_bf16 v[20:23], v[206:209], v[148:151], v[20:23]
	ds_read_b128 v[186:189], v245 offset:22528
	v_mfma_f32_16x16x32_bf16 v[20:23], v[202:205], v[144:147], v[20:23]
	ds_read_b128 v[190:193], v246 offset:22528
	v_mfma_f32_16x16x32_bf16 v[28:31], v[202:205], v[152:155], v[28:31]
	v_mfma_f32_16x16x32_bf16 v[28:31], v[206:209], v[156:159], v[28:31]
	v_mfma_f32_16x16x32_bf16 v[24:27], v[198:201], v[156:159], v[24:27]
	v_mfma_f32_16x16x32_bf16 v[24:27], v[194:197], v[152:155], v[24:27]
	s_waitcnt lgkmcnt(8)
	v_mfma_f32_16x16x32_bf16 v[32:35], v[210:213], v[128:131], v[32:35]
	v_mfma_f32_16x16x32_bf16 v[32:35], v[214:217], v[132:135], v[32:35]
	s_add_i32 m0, s35, 0x0
	v_mfma_f32_16x16x32_bf16 v[36:39], v[222:225], v[132:135], v[36:39]
	global_load_lds_dwordx4 v249, s[30:31]
	v_mfma_f32_16x16x32_bf16 v[36:39], v[218:221], v[128:131], v[36:39]
	v_mfma_f32_16x16x32_bf16 v[44:47], v[218:221], v[136:139], v[44:47]
	s_add_i32 m0, s35, 0x2000
	v_mfma_f32_16x16x32_bf16 v[44:47], v[222:225], v[140:143], v[44:47]
	global_load_lds_dwordx4 v250, s[30:31]
	v_mfma_f32_16x16x32_bf16 v[40:43], v[214:217], v[140:143], v[40:43]
	v_mfma_f32_16x16x32_bf16 v[40:43], v[210:213], v[136:139], v[40:43]
	s_add_i32 m0, s35, 0x10000
	v_mfma_f32_16x16x32_bf16 v[48:51], v[210:213], v[144:147], v[48:51]
	global_load_lds_dwordx4 v251, s[32:33]
	v_mfma_f32_16x16x32_bf16 v[48:51], v[214:217], v[148:151], v[48:51]
	v_mfma_f32_16x16x32_bf16 v[52:55], v[222:225], v[148:151], v[52:55]
	s_add_i32 m0, s35, 0x12000
	v_mfma_f32_16x16x32_bf16 v[52:55], v[218:221], v[144:147], v[52:55]
	global_load_lds_dwordx4 v252, s[32:33]
	v_mfma_f32_16x16x32_bf16 v[60:63], v[218:221], v[152:155], v[60:63]
	v_mfma_f32_16x16x32_bf16 v[60:63], v[222:225], v[156:159], v[60:63]
	v_mfma_f32_16x16x32_bf16 v[56:59], v[214:217], v[156:159], v[56:59]
	v_mfma_f32_16x16x32_bf16 v[56:59], v[210:213], v[152:155], v[56:59]
	s_waitcnt vmcnt(8)
	s_waitcnt lgkmcnt(0)
	s_barrier
	v_mfma_f32_16x16x32_bf16 v[96:99], v[210:213], v[160:163], v[96:99]
	ds_read_b128 v[128:131], v245 offset:32768
	v_mfma_f32_16x16x32_bf16 v[96:99], v[214:217], v[164:167], v[96:99]
	ds_read_b128 v[132:135], v246 offset:32768
	v_mfma_f32_16x16x32_bf16 v[100:103], v[222:225], v[164:167], v[100:103]
	ds_read_b128 v[136:139], v245 offset:34816
	v_mfma_f32_16x16x32_bf16 v[100:103], v[218:221], v[160:163], v[100:103]
	ds_read_b128 v[140:143], v246 offset:34816
	v_mfma_f32_16x16x32_bf16 v[108:111], v[218:221], v[168:171], v[108:111]
	ds_read_b128 v[144:147], v245 offset:36864
	v_mfma_f32_16x16x32_bf16 v[108:111], v[222:225], v[172:175], v[108:111]
	ds_read_b128 v[148:151], v246 offset:36864
	v_mfma_f32_16x16x32_bf16 v[104:107], v[214:217], v[172:175], v[104:107]
	ds_read_b128 v[152:155], v245 offset:38912
	v_mfma_f32_16x16x32_bf16 v[104:107], v[210:213], v[168:171], v[104:107]
	ds_read_b128 v[156:159], v246 offset:38912
	v_mfma_f32_16x16x32_bf16 v[112:115], v[210:213], v[176:179], v[112:115]
	v_mfma_f32_16x16x32_bf16 v[112:115], v[214:217], v[180:183], v[112:115]
	v_mfma_f32_16x16x32_bf16 v[116:119], v[222:225], v[180:183], v[116:119]
	v_mfma_f32_16x16x32_bf16 v[116:119], v[218:221], v[176:179], v[116:119]
	v_mfma_f32_16x16x32_bf16 v[124:127], v[218:221], v[186:189], v[124:127]
	v_mfma_f32_16x16x32_bf16 v[124:127], v[222:225], v[190:193], v[124:127]
	v_mfma_f32_16x16x32_bf16 v[120:123], v[214:217], v[190:193], v[120:123]
	v_mfma_f32_16x16x32_bf16 v[120:123], v[210:213], v[186:189], v[120:123]
	v_mfma_f32_16x16x32_bf16 v[64:67], v[194:197], v[160:163], v[64:67]
	ds_read_b128 v[210:213], v247 offset:49152
	v_mfma_f32_16x16x32_bf16 v[64:67], v[198:201], v[164:167], v[64:67]
	ds_read_b128 v[214:217], v248 offset:49152
	v_mfma_f32_16x16x32_bf16 v[68:71], v[206:209], v[164:167], v[68:71]
	ds_read_b128 v[218:221], v247 offset:51200
	v_mfma_f32_16x16x32_bf16 v[68:71], v[202:205], v[160:163], v[68:71]
	ds_read_b128 v[222:225], v248 offset:51200
	v_mfma_f32_16x16x32_bf16 v[76:79], v[202:205], v[168:171], v[76:79]
	s_add_i32 m0, s35, 0x4000
	v_mfma_f32_16x16x32_bf16 v[76:79], v[206:209], v[172:175], v[76:79]
	global_load_lds_dwordx4 v249, s[56:57]
	v_mfma_f32_16x16x32_bf16 v[72:75], v[198:201], v[172:175], v[72:75]
	s_add_i32 m0, s35, 0x6000
	v_mfma_f32_16x16x32_bf16 v[72:75], v[194:197], v[168:171], v[72:75]
	global_load_lds_dwordx4 v250, s[56:57]
	v_mfma_f32_16x16x32_bf16 v[80:83], v[194:197], v[176:179], v[80:83]
	s_add_i32 m0, s35, 0x14000
	v_mfma_f32_16x16x32_bf16 v[80:83], v[198:201], v[180:183], v[80:83]
	global_load_lds_dwordx4 v251, s[58:59]
	v_mfma_f32_16x16x32_bf16 v[84:87], v[206:209], v[180:183], v[84:87]
	s_add_i32 m0, s35, 0x16000
	v_mfma_f32_16x16x32_bf16 v[84:87], v[202:205], v[176:179], v[84:87]
	global_load_lds_dwordx4 v252, s[58:59]
	v_mfma_f32_16x16x32_bf16 v[92:95], v[202:205], v[186:189], v[92:95]
	s_add_u32 s30, s30, s4
	s_addc_u32 s31, s31, s5
	v_mfma_f32_16x16x32_bf16 v[92:95], v[206:209], v[190:193], v[92:95]
	s_add_u32 s56, s56, s4
	s_addc_u32 s57, s57, s5
	v_mfma_f32_16x16x32_bf16 v[88:91], v[198:201], v[190:193], v[88:91]
	s_add_u32 s32, s32, s4
	s_addc_u32 s33, s33, s5
	v_mfma_f32_16x16x32_bf16 v[88:91], v[194:197], v[186:189], v[88:91]
	s_add_u32 s58, s58, s4
	s_addc_u32 s59, s59, s5
	s_waitcnt vmcnt(8)
	s_waitcnt lgkmcnt(0)
	s_barrier
; #define PG8_STAGE(bufoff, gbase, voff) do { _Pragma("unroll") for (int _i = 0; _i < 2; ++_i) \
;         __builtin_amdgcn_global_load_lds((const unsigned*)((const char*)(gbase) + (voff)[_i]), (PG8_LAS unsigned*)(lds + (bufoff) + ldsw + _i * 8192), 16, 0, 0); } while (0)
; #define PG8_LDA(dst, b, h) do { _Pragma("unroll") for (int m = 0; m < 4; ++m) _Pragma("unroll") for (int k = 0; k < 2; ++k) dst[m][k] = *(const PG8_LAS bf16x8*)(lds + PG8_SA(b, h) + aoff + m * 2048 + k * 1024); } while (0)
; #define PG8_WAIT_V(n) asm volatile("s_waitcnt vmcnt(" #n ")" ::: "memory")
; template <class Epi, class Sched, bool ALIGN_EPI = false, bool SP2 = false>
; __device__ __forceinline__ void gemm_phase(PG8_LAS unsigned char* lds, const Gemm g, const Sched& S, const Epi& E) {
;     ...
;         const bool has_next = S.next(ui + 1, nxt);
;         const char* nA = has_next ? (const char*)g.A + (size_t)nxt.pm * tstep : cA; const char* nB = has_next ? (const char*)g.Bt + (size_t)nxt.pn * tstep : cB;
;         for (int t = 0; t < nt; t += 2) {
;             const bool last = (t == nt - 2);
;             const char* a1 = cA + (size_t)(t + 1) * kstep;
;             const char* a2 = last ? nA : cA + (size_t)(t + 2) * kstep; const char* b2 = last ? nB : cB + (size_t)(t + 2) * kstep;
;             const char* a3 = a2 + kstep; const char* b3 = b2 + kstep;
;     ...
;             PG8_LDB(B0, 0, 0); PG8_LDB(B1, 0, 1); PG8_SCHED; PG8_LDA(At, 0, 0); PG8_STAGE(PG8_SA(1, 1), a1 + hstep, voffA);
;             PG8_WAIT_V(8); PG8_WAIT_L(0); PG8_BAR; PG8_MMA(0, 0, At, B0); PG8_MMA(0, 1, At, B1); PG8_BAR; PG8_SCHED;
;             PG8_LDA(At, 0, 1); PG8_STAGE(PG8_SB(0, 0), b2, voffB); PG8_STAGE(PG8_SB(0, 1), b2 + hstep, voffB); PG8_STAGE(PG8_SA(0, 0), a2, voffA);
;             PG8_WAIT_V(8); PG8_WAIT_L(0); PG8_BAR; PG8_MMA(1, 0, At, B0); PG8_MMA(1, 1, At, B1); PG8_BAR; PG8_SCHED;
;             PG8_LDB(B0, 1, 0); PG8_LDB(B1, 1, 1); PG8_SCHED; PG8_LDA(At, 1, 0); PG8_STAGE(PG8_SA(0, 1), a2 + hstep, voffA);
;             PG8_WAIT_V(8); PG8_WAIT_L(0); PG8_BAR; PG8_MMA(0, 0, At, B0); PG8_MMA(0, 1, At, B1); PG8_BAR; PG8_SCHED;
;             PG8_LDA(At, 1, 1); PG8_STAGE(PG8_SB(1, 0), b3, voffB); PG8_STAGE(PG8_SB(1, 1), b3 + hstep, voffB); PG8_STAGE(PG8_SA(1, 0), a3, voffA);
;             PG8_WAIT_V(8); PG8_WAIT_L(0); PG8_BAR; PG8_MMA(1, 0, At, B0); PG8_MMA(1, 1, At, B1); PG8_BAR; PG8_SCHED;
	v_mfma_f32_16x16x32_bf16 v[32:35], v[210:213], v[128:131], v[32:35]
	ds_read_b128 v[194:197], v247 offset:32768
	v_mfma_f32_16x16x32_bf16 v[32:35], v[214:217], v[132:135], v[32:35]
	ds_read_b128 v[198:201], v248 offset:32768
	v_mfma_f32_16x16x32_bf16 v[36:39], v[222:225], v[132:135], v[36:39]
	ds_read_b128 v[202:205], v247 offset:34816
	v_mfma_f32_16x16x32_bf16 v[36:39], v[218:221], v[128:131], v[36:39]
	ds_read_b128 v[206:209], v248 offset:34816
	v_mfma_f32_16x16x32_bf16 v[44:47], v[218:221], v[136:139], v[44:47]
	ds_read_b128 v[160:163], v245 offset:49152
	v_mfma_f32_16x16x32_bf16 v[44:47], v[222:225], v[140:143], v[44:47]
	ds_read_b128 v[164:167], v246 offset:49152
	v_mfma_f32_16x16x32_bf16 v[40:43], v[214:217], v[140:143], v[40:43]
	ds_read_b128 v[168:171], v245 offset:51200
	v_mfma_f32_16x16x32_bf16 v[40:43], v[210:213], v[136:139], v[40:43]
	ds_read_b128 v[172:175], v246 offset:51200
	v_mfma_f32_16x16x32_bf16 v[48:51], v[210:213], v[144:147], v[48:51]
	ds_read_b128 v[176:179], v245 offset:53248
	v_mfma_f32_16x16x32_bf16 v[48:51], v[214:217], v[148:151], v[48:51]
	ds_read_b128 v[180:183], v246 offset:53248
	v_mfma_f32_16x16x32_bf16 v[52:55], v[222:225], v[148:151], v[52:55]
	ds_read_b128 v[186:189], v245 offset:55296
	v_mfma_f32_16x16x32_bf16 v[52:55], v[218:221], v[144:147], v[52:55]
	ds_read_b128 v[190:193], v246 offset:55296
	v_mfma_f32_16x16x32_bf16 v[60:63], v[218:221], v[152:155], v[60:63]
	v_mfma_f32_16x16x32_bf16 v[60:63], v[222:225], v[156:159], v[60:63]
	v_mfma_f32_16x16x32_bf16 v[56:59], v[214:217], v[156:159], v[56:59]
	v_mfma_f32_16x16x32_bf16 v[56:59], v[210:213], v[152:155], v[56:59]
	s_waitcnt lgkmcnt(8)
	v_mfma_f32_16x16x32_bf16 v[0:3], v[194:197], v[128:131], v[0:3]
	v_mfma_f32_16x16x32_bf16 v[0:3], v[198:201], v[132:135], v[0:3]
	s_add_i32 m0, s35, 0x8000
	v_mfma_f32_16x16x32_bf16 v[4:7], v[206:209], v[132:135], v[4:7]
	global_load_lds_dwordx4 v249, s[30:31]
	v_mfma_f32_16x16x32_bf16 v[4:7], v[202:205], v[128:131], v[4:7]
	v_mfma_f32_16x16x32_bf16 v[12:15], v[202:205], v[136:139], v[12:15]
	s_add_i32 m0, s35, 0xa000
	v_mfma_f32_16x16x32_bf16 v[12:15], v[206:209], v[140:143], v[12:15]
	global_load_lds_dwordx4 v250, s[30:31]
	v_mfma_f32_16x16x32_bf16 v[8:11], v[198:201], v[140:143], v[8:11]
	v_mfma_f32_16x16x32_bf16 v[8:11], v[194:197], v[136:139], v[8:11]
	s_add_i32 m0, s35, 0x1c000
	v_mfma_f32_16x16x32_bf16 v[16:19], v[194:197], v[144:147], v[16:19]
	global_load_lds_dwordx4 v251, s[58:59]
	v_mfma_f32_16x16x32_bf16 v[16:19], v[198:201], v[148:151], v[16:19]
	v_mfma_f32_16x16x32_bf16 v[20:23], v[206:209], v[148:151], v[20:23]
	s_add_i32 m0, s35, 0x1e000
	v_mfma_f32_16x16x32_bf16 v[20:23], v[202:205], v[144:147], v[20:23]
	global_load_lds_dwordx4 v252, s[58:59]
	v_mfma_f32_16x16x32_bf16 v[28:31], v[202:205], v[152:155], v[28:31]
	v_mfma_f32_16x16x32_bf16 v[28:31], v[206:209], v[156:159], v[28:31]
	v_mfma_f32_16x16x32_bf16 v[24:27], v[198:201], v[156:159], v[24:27]
	v_mfma_f32_16x16x32_bf16 v[24:27], v[194:197], v[152:155], v[24:27]
	s_waitcnt vmcnt(8)
	s_waitcnt lgkmcnt(0)
	s_barrier
	v_mfma_f32_16x16x32_bf16 v[64:67], v[194:197], v[160:163], v[64:67]
	ds_read_b128 v[128:131], v245 offset:0
	v_mfma_f32_16x16x32_bf16 v[64:67], v[198:201], v[164:167], v[64:67]
	ds_read_b128 v[132:135], v246 offset:0
	v_mfma_f32_16x16x32_bf16 v[68:71], v[206:209], v[164:167], v[68:71]
	ds_read_b128 v[136:139], v245 offset:2048
	v_mfma_f32_16x16x32_bf16 v[68:71], v[202:205], v[160:163], v[68:71]
	ds_read_b128 v[140:143], v246 offset:2048
	v_mfma_f32_16x16x32_bf16 v[76:79], v[202:205], v[168:171], v[76:79]
	ds_read_b128 v[144:147], v245 offset:4096
	v_mfma_f32_16x16x32_bf16 v[76:79], v[206:209], v[172:175], v[76:79]
	ds_read_b128 v[148:151], v246 offset:4096
	v_mfma_f32_16x16x32_bf16 v[72:75], v[198:201], v[172:175], v[72:75]
	ds_read_b128 v[152:155], v245 offset:6144
	v_mfma_f32_16x16x32_bf16 v[72:75], v[194:197], v[168:171], v[72:75]
	ds_read_b128 v[156:159], v246 offset:6144
	v_mfma_f32_16x16x32_bf16 v[80:83], v[194:197], v[176:179], v[80:83]
	v_mfma_f32_16x16x32_bf16 v[80:83], v[198:201], v[180:183], v[80:83]
	v_mfma_f32_16x16x32_bf16 v[84:87], v[206:209], v[180:183], v[84:87]
	v_mfma_f32_16x16x32_bf16 v[84:87], v[202:205], v[176:179], v[84:87]
	v_mfma_f32_16x16x32_bf16 v[92:95], v[202:205], v[186:189], v[92:95]
	v_mfma_f32_16x16x32_bf16 v[92:95], v[206:209], v[190:193], v[92:95]
	v_mfma_f32_16x16x32_bf16 v[88:91], v[198:201], v[190:193], v[88:91]
	v_mfma_f32_16x16x32_bf16 v[88:91], v[194:197], v[186:189], v[88:91]
	v_mfma_f32_16x16x32_bf16 v[96:99], v[210:213], v[160:163], v[96:99]
	ds_read_b128 v[194:197], v247 offset:0
	v_mfma_f32_16x16x32_bf16 v[96:99], v[214:217], v[164:167], v[96:99]
	ds_read_b128 v[198:201], v248 offset:0
	v_mfma_f32_16x16x32_bf16 v[100:103], v[222:225], v[164:167], v[100:103]
	ds_read_b128 v[202:205], v247 offset:2048
	v_mfma_f32_16x16x32_bf16 v[100:103], v[218:221], v[160:163], v[100:103]
	ds_read_b128 v[206:209], v248 offset:2048
	v_mfma_f32_16x16x32_bf16 v[108:111], v[218:221], v[168:171], v[108:111]
	s_add_i32 m0, s35, 0xc000
	v_mfma_f32_16x16x32_bf16 v[108:111], v[222:225], v[172:175], v[108:111]
	global_load_lds_dwordx4 v249, s[56:57]
	v_mfma_f32_16x16x32_bf16 v[104:107], v[214:217], v[172:175], v[104:107]
	s_add_i32 m0, s35, 0xe000
	v_mfma_f32_16x16x32_bf16 v[104:107], v[210:213], v[168:171], v[104:107]
	global_load_lds_dwordx4 v250, s[56:57]
	v_mfma_f32_16x16x32_bf16 v[112:115], v[210:213], v[176:179], v[112:115]
	s_add_i32 m0, s35, 0x18000
	v_mfma_f32_16x16x32_bf16 v[112:115], v[214:217], v[180:183], v[112:115]
	global_load_lds_dwordx4 v251, s[32:33]
	v_mfma_f32_16x16x32_bf16 v[116:119], v[222:225], v[180:183], v[116:119]
	s_add_i32 m0, s35, 0x1a000
	v_mfma_f32_16x16x32_bf16 v[116:119], v[218:221], v[176:179], v[116:119]
	global_load_lds_dwordx4 v252, s[32:33]
	v_mfma_f32_16x16x32_bf16 v[124:127], v[218:221], v[186:189], v[124:127]
	s_add_u32 s30, s30, s4
	s_addc_u32 s31, s31, s5
	v_mfma_f32_16x16x32_bf16 v[124:127], v[222:225], v[190:193], v[124:127]
	s_add_u32 s56, s56, s4
	s_addc_u32 s57, s57, s5
	v_mfma_f32_16x16x32_bf16 v[120:123], v[214:217], v[190:193], v[120:123]
	s_add_u32 s32, s32, s4
	s_addc_u32 s33, s33, s5
	v_mfma_f32_16x16x32_bf16 v[120:123], v[210:213], v[186:189], v[120:123]
	s_add_u32 s58, s58, s4
	s_addc_u32 s59, s59, s5
	s_add_i32 s34, s34, -1
	s_cmp_lg_u32 s34, 1
	s_cbranch_scc1 .Lp5_nosw1
	s_add_u32 s45, s16, 1
	s_and_b32 s40, s45, 1
	s_lshl_b32 s4, s40, 8
	s_sub_u32 s4, 128, s4
	s_sub_u32 s5, 0, s40
	s_mul_i32 s8, s40, 3968
	s_add_u32 s30, s26, s8
	s_addc_u32 s31, s27, 0
	s_add_u32 s32, s28, s8
	s_addc_u32 s33, s29, 0
	s_add_u32 s56, s30, 0x80000
	s_addc_u32 s57, s31, 0
	s_add_u32 s58, s32, 0x80000
	s_addc_u32 s59, s33, 0

; #define PG8_STAGE(bufoff, gbase, voff) do { _Pragma("unroll") for (int _i = 0; _i < 2; ++_i) \
;         __builtin_amdgcn_global_load_lds((const unsigned*)((const char*)(gbase) + (voff)[_i]), (PG8_LAS unsigned*)(lds + (bufoff) + ldsw + _i * 8192), 16, 0, 0); } while (0)
; #define PG8_LDA(dst, b, h) do { _Pragma("unroll") for (int m = 0; m < 4; ++m) _Pragma("unroll") for (int k = 0; k < 2; ++k) dst[m][k] = *(const PG8_LAS bf16x8*)(lds + PG8_SA(b, h) + aoff + m * 2048 + k * 1024); } while (0)
; #define PG8_LDB(dst, b, h) do { _Pragma("unroll") for (int n = 0; n < 2; ++n) _Pragma("unroll") for (int k = 0; k < 2; ++k) dst[n][k] = *(const PG8_LAS bf16x8*)(lds + PG8_SB(b, h) + boff + n * 2048 + k * 1024); } while (0)
; #define PG8_MMA(ai, bj, At, Bt) do { __builtin_amdgcn_s_setprio(1); _Pragma("unroll") for (int m = 0; m < 4; ++m) _Pragma("unroll") for (int n = 0; n < 2; ++n) _Pragma("unroll") for (int k = 0; k < 2; ++k) \
;         acc[ai][bj][m][n] = __builtin_amdgcn_mfma_f32_16x16x32_bf16(Bt[n][k], At[m][k], acc[ai][bj][m][n], 0, 0, 0); __builtin_amdgcn_s_setprio(0); } while (0)
; #define PG8_WAIT_V(n) asm volatile("s_waitcnt vmcnt(" #n ")" ::: "memory")
; template <class Epi, class Sched, bool ALIGN_EPI = false, bool SP2 = false>
; __device__ __forceinline__ void gemm_phase(PG8_LAS unsigned char* lds, const Gemm g, const Sched& S, const Epi& E) {
;     ...
;             PG8_LDB(B0, 0, 0); PG8_LDB(B1, 0, 1); PG8_SCHED; PG8_LDA(At, 0, 0); PG8_STAGE(PG8_SA(1, 1), a1 + hstep, voffA);
;             PG8_WAIT_V(8); PG8_WAIT_L(0); PG8_BAR; PG8_MMA(0, 0, At, B0); PG8_MMA(0, 1, At, B1); PG8_BAR; PG8_SCHED;
;             PG8_LDA(At, 0, 1); PG8_STAGE(PG8_SB(0, 0), b2, voffB); PG8_STAGE(PG8_SB(0, 1), b2 + hstep, voffB); PG8_STAGE(PG8_SA(0, 0), a2, voffA);
;             PG8_WAIT_V(8); PG8_WAIT_L(0); PG8_BAR; PG8_MMA(1, 0, At, B0); PG8_MMA(1, 1, At, B1); PG8_BAR; PG8_SCHED;
;             PG8_LDB(B0, 1, 0); PG8_LDB(B1, 1, 1); PG8_SCHED; PG8_LDA(At, 1, 0); PG8_STAGE(PG8_SA(0, 1), a2 + hstep, voffA);
;             PG8_WAIT_V(8); PG8_WAIT_L(0); PG8_BAR; PG8_MMA(0, 0, At, B0); PG8_MMA(0, 1, At, B1); PG8_BAR; PG8_SCHED;
;             PG8_LDA(At, 1, 1); PG8_STAGE(PG8_SB(1, 0), b3, voffB); PG8_STAGE(PG8_SB(1, 1), b3 + hstep, voffB); PG8_STAGE(PG8_SA(1, 0), a3, voffA);
;             PG8_WAIT_V(8); PG8_WAIT_L(0); PG8_BAR; PG8_MMA(1, 0, At, B0); PG8_MMA(1, 1, At, B1); PG8_BAR; PG8_SCHED;
.Lp6_kloop0:
	s_waitcnt vmcnt(8)
	s_waitcnt lgkmcnt(0)
	s_barrier
	v_mfma_f32_16x16x32_bf16 v[0:3], v[194:197], v[128:131], v[0:3]
	ds_read_b128 v[210:213], v247 offset:16384
	v_mfma_f32_16x16x32_bf16 v[0:3], v[198:201], v[132:135], v[0:3]
	ds_read_b128 v[214:217], v248 offset:16384
	v_mfma_f32_16x16x32_bf16 v[4:7], v[206:209], v[132:135], v[4:7]
	ds_read_b128 v[218:221], v247 offset:18432
	v_mfma_f32_16x16x32_bf16 v[4:7], v[202:205], v[128:131], v[4:7]
	ds_read_b128 v[222:225], v248 offset:18432
	v_mfma_f32_16x16x32_bf16 v[12:15], v[202:205], v[136:139], v[12:15]
	s_add_i32 m0, s35, 0x0
	v_mfma_f32_16x16x32_bf16 v[12:15], v[206:209], v[140:143], v[12:15]
	global_load_lds_dwordx4 v249, s[30:31]
	v_mfma_f32_16x16x32_bf16 v[8:11], v[198:201], v[140:143], v[8:11]
	s_add_i32 m0, s35, 0x2000
	v_mfma_f32_16x16x32_bf16 v[8:11], v[194:197], v[136:139], v[8:11]
	global_load_lds_dwordx4 v250, s[30:31]
	v_mfma_f32_16x16x32_bf16 v[16:19], v[194:197], v[144:147], v[16:19]
	s_add_i32 m0, s35, 0x10000
	v_mfma_f32_16x16x32_bf16 v[16:19], v[198:201], v[148:151], v[16:19]
	global_load_lds_dwordx4 v251, s[32:33]
	v_mfma_f32_16x16x32_bf16 v[20:23], v[206:209], v[148:151], v[20:23]
	s_add_i32 m0, s35, 0x12000
	v_mfma_f32_16x16x32_bf16 v[20:23], v[202:205], v[144:147], v[20:23]
	global_load_lds_dwordx4 v252, s[32:33]
	v_mfma_f32_16x16x32_bf16 v[28:31], v[202:205], v[152:155], v[28:31]
	ds_read_b128 v[160:163], v245 offset:16384
	v_mfma_f32_16x16x32_bf16 v[28:31], v[206:209], v[156:159], v[28:31]
	ds_read_b128 v[164:167], v246 offset:16384
	v_mfma_f32_16x16x32_bf16 v[24:27], v[198:201], v[156:159], v[24:27]
	ds_read_b128 v[168:171], v245 offset:18432
	v_mfma_f32_16x16x32_bf16 v[24:27], v[194:197], v[152:155], v[24:27]
	ds_read_b128 v[172:175], v246 offset:18432
	s_waitcnt lgkmcnt(4)
	v_mfma_f32_16x16x32_bf16 v[32:35], v[210:213], v[128:131], v[32:35]
	ds_read_b128 v[176:179], v245 offset:20480
	v_mfma_f32_16x16x32_bf16 v[32:35], v[214:217], v[132:135], v[32:35]
	ds_read_b128 v[180:183], v246 offset:20480
	v_mfma_f32_16x16x32_bf16 v[36:39], v[222:225], v[132:135], v[36:39]
	ds_read_b128 v[186:189], v245 offset:22528
	v_mfma_f32_16x16x32_bf16 v[36:39], v[218:221], v[128:131], v[36:39]
	ds_read_b128 v[190:193], v246 offset:22528
	v_mfma_f32_16x16x32_bf16 v[44:47], v[218:221], v[136:139], v[44:47]
	v_mfma_f32_16x16x32_bf16 v[44:47], v[222:225], v[140:143], v[44:47]
	v_mfma_f32_16x16x32_bf16 v[40:43], v[214:217], v[140:143], v[40:43]
	v_mfma_f32_16x16x32_bf16 v[40:43], v[210:213], v[136:139], v[40:43]
	v_mfma_f32_16x16x32_bf16 v[48:51], v[210:213], v[144:147], v[48:51]
	v_mfma_f32_16x16x32_bf16 v[48:51], v[214:217], v[148:151], v[48:51]
	v_mfma_f32_16x16x32_bf16 v[52:55], v[222:225], v[148:151], v[52:55]
	v_mfma_f32_16x16x32_bf16 v[52:55], v[218:221], v[144:147], v[52:55]
	v_mfma_f32_16x16x32_bf16 v[60:63], v[218:221], v[152:155], v[60:63]
	v_mfma_f32_16x16x32_bf16 v[60:63], v[222:225], v[156:159], v[60:63]
	v_mfma_f32_16x16x32_bf16 v[56:59], v[214:217], v[156:159], v[56:59]
	v_mfma_f32_16x16x32_bf16 v[56:59], v[210:213], v[152:155], v[56:59]
	s_waitcnt vmcnt(8)
	s_waitcnt lgkmcnt(0)
	s_barrier
	v_mfma_f32_16x16x32_bf16 v[96:99], v[210:213], v[160:163], v[96:99]
	s_add_i32 m0, s35, 0x4000
	v_mfma_f32_16x16x32_bf16 v[96:99], v[214:217], v[164:167], v[96:99]
	global_load_lds_dwordx4 v249, s[56:57]
	v_mfma_f32_16x16x32_bf16 v[100:103], v[222:225], v[164:167], v[100:103]
	s_add_i32 m0, s35, 0x6000
	v_mfma_f32_16x16x32_bf16 v[100:103], v[218:221], v[160:163], v[100:103]
	global_load_lds_dwordx4 v250, s[56:57]
	v_mfma_f32_16x16x32_bf16 v[108:111], v[218:221], v[168:171], v[108:111]
	s_add_i32 m0, s35, 0x14000
	v_mfma_f32_16x16x32_bf16 v[108:111], v[222:225], v[172:175], v[108:111]
	global_load_lds_dwordx4 v251, s[58:59]
	v_mfma_f32_16x16x32_bf16 v[104:107], v[214:217], v[172:175], v[104:107]
	s_add_i32 m0, s35, 0x16000
	v_mfma_f32_16x16x32_bf16 v[104:107], v[210:213], v[168:171], v[104:107]
	global_load_lds_dwordx4 v252, s[58:59]
	v_mfma_f32_16x16x32_bf16 v[112:115], v[210:213], v[176:179], v[112:115]
	ds_read_b128 v[128:131], v245 offset:32768
	v_mfma_f32_16x16x32_bf16 v[112:115], v[214:217], v[180:183], v[112:115]
	ds_read_b128 v[132:135], v246 offset:32768
	v_mfma_f32_16x16x32_bf16 v[116:119], v[222:225], v[180:183], v[116:119]
	ds_read_b128 v[136:139], v245 offset:34816
	v_mfma_f32_16x16x32_bf16 v[116:119], v[218:221], v[176:179], v[116:119]
	ds_read_b128 v[140:143], v246 offset:34816
	v_mfma_f32_16x16x32_bf16 v[124:127], v[218:221], v[186:189], v[124:127]
	ds_read_b128 v[144:147], v245 offset:36864
	v_mfma_f32_16x16x32_bf16 v[124:127], v[222:225], v[190:193], v[124:127]
	ds_read_b128 v[148:151], v246 offset:36864
	v_mfma_f32_16x16x32_bf16 v[120:123], v[214:217], v[190:193], v[120:123]
	ds_read_b128 v[152:155], v245 offset:38912
	v_mfma_f32_16x16x32_bf16 v[120:123], v[210:213], v[186:189], v[120:123]
	ds_read_b128 v[156:159], v246 offset:38912
	v_mfma_f32_16x16x32_bf16 v[64:67], v[194:197], v[160:163], v[64:67]
	ds_read_b128 v[210:213], v247 offset:49152
	v_mfma_f32_16x16x32_bf16 v[64:67], v[198:201], v[164:167], v[64:67]
	ds_read_b128 v[214:217], v248 offset:49152
	v_mfma_f32_16x16x32_bf16 v[68:71], v[206:209], v[164:167], v[68:71]
	ds_read_b128 v[218:221], v247 offset:51200
	v_mfma_f32_16x16x32_bf16 v[68:71], v[202:205], v[160:163], v[68:71]
	ds_read_b128 v[222:225], v248 offset:51200
	v_mfma_f32_16x16x32_bf16 v[76:79], v[202:205], v[168:171], v[76:79]
	s_add_u32 s30, s30, s4
	s_addc_u32 s31, s31, s5
	v_mfma_f32_16x16x32_bf16 v[76:79], v[206:209], v[172:175], v[76:79]
	s_add_u32 s56, s56, s4
	s_addc_u32 s57, s57, s5
	v_mfma_f32_16x16x32_bf16 v[72:75], v[198:201], v[172:175], v[72:75]
	s_add_u32 s32, s32, s4
	s_addc_u32 s33, s33, s5
	v_mfma_f32_16x16x32_bf16 v[72:75], v[194:197], v[168:171], v[72:75]
	s_add_u32 s58, s58, s4
	s_addc_u32 s59, s59, s5
	v_mfma_f32_16x16x32_bf16 v[80:83], v[194:197], v[176:179], v[80:83]
	v_mfma_f32_16x16x32_bf16 v[80:83], v[198:201], v[180:183], v[80:83]
	v_mfma_f32_16x16x32_bf16 v[84:87], v[206:209], v[180:183], v[84:87]
	v_mfma_f32_16x16x32_bf16 v[84:87], v[202:205], v[176:179], v[84:87]
	v_mfma_f32_16x16x32_bf16 v[92:95], v[202:205], v[186:189], v[92:95]
	v_mfma_f32_16x16x32_bf16 v[92:95], v[206:209], v[190:193], v[92:95]
	v_mfma_f32_16x16x32_bf16 v[88:91], v[198:201], v[190:193], v[88:91]
	v_mfma_f32_16x16x32_bf16 v[88:91], v[194:197], v[186:189], v[88:91]
	s_waitcnt vmcnt(8)
	s_waitcnt lgkmcnt(0)
	s_barrier
; #define PG8_STAGE(bufoff, gbase, voff) do { _Pragma("unroll") for (int _i = 0; _i < 2; ++_i) \
;         __builtin_amdgcn_global_load_lds((const unsigned*)((const char*)(gbase) + (voff)[_i]), (PG8_LAS unsigned*)(lds + (bufoff) + ldsw + _i * 8192), 16, 0, 0); } while (0)
; #define PG8_LDA(dst, b, h) do { _Pragma("unroll") for (int m = 0; m < 4; ++m) _Pragma("unroll") for (int k = 0; k < 2; ++k) dst[m][k] = *(const PG8_LAS bf16x8*)(lds + PG8_SA(b, h) + aoff + m * 2048 + k * 1024); } while (0)
; #define PG8_WAIT_V(n) asm volatile("s_waitcnt vmcnt(" #n ")" ::: "memory")
; template <class Epi, class Sched, bool ALIGN_EPI = false, bool SP2 = false>
; __device__ __forceinline__ void gemm_phase(PG8_LAS unsigned char* lds, const Gemm g, const Sched& S, const Epi& E) {
;     ...
;         const bool has_next = S.next(ui + 1, nxt);
;         const char* nA = has_next ? (const char*)g.A + (size_t)nxt.pm * tstep : cA; const char* nB = has_next ? (const char*)g.Bt + (size_t)nxt.pn * tstep : cB;
;         for (int t = 0; t < nt; t += 2) {
;             const bool last = (t == nt - 2);
;             const char* a1 = cA + (size_t)(t + 1) * kstep;
;             const char* a2 = last ? nA : cA + (size_t)(t + 2) * kstep; const char* b2 = last ? nB : cB + (size_t)(t + 2) * kstep;
;             const char* a3 = a2 + kstep; const char* b3 = b2 + kstep;
;     ...
;             PG8_LDB(B0, 0, 0); PG8_LDB(B1, 0, 1); PG8_SCHED; PG8_LDA(At, 0, 0); PG8_STAGE(PG8_SA(1, 1), a1 + hstep, voffA);
;             PG8_WAIT_V(8); PG8_WAIT_L(0); PG8_BAR; PG8_MMA(0, 0, At, B0); PG8_MMA(0, 1, At, B1); PG8_BAR; PG8_SCHED;
;             PG8_LDA(At, 0, 1); PG8_STAGE(PG8_SB(0, 0), b2, voffB); PG8_STAGE(PG8_SB(0, 1), b2 + hstep, voffB); PG8_STAGE(PG8_SA(0, 0), a2, voffA);
;             PG8_WAIT_V(8); PG8_WAIT_L(0); PG8_BAR; PG8_MMA(1, 0, At, B0); PG8_MMA(1, 1, At, B1); PG8_BAR; PG8_SCHED;
;             PG8_LDB(B0, 1, 0); PG8_LDB(B1, 1, 1); PG8_SCHED; PG8_LDA(At, 1, 0); PG8_STAGE(PG8_SA(0, 1), a2 + hstep, voffA);
;             PG8_WAIT_V(8); PG8_WAIT_L(0); PG8_BAR; PG8_MMA(0, 0, At, B0); PG8_MMA(0, 1, At, B1); PG8_BAR; PG8_SCHED;
;             PG8_LDA(At, 1, 1); PG8_STAGE(PG8_SB(1, 0), b3, voffB); PG8_STAGE(PG8_SB(1, 1), b3 + hstep, voffB); PG8_STAGE(PG8_SA(1, 0), a3, voffA);
;             PG8_WAIT_V(8); PG8_WAIT_L(0); PG8_BAR; PG8_MMA(1, 0, At, B0); PG8_MMA(1, 1, At, B1); PG8_BAR; PG8_SCHED;
	v_mfma_f32_16x16x32_bf16 v[32:35], v[210:213], v[128:131], v[32:35]
	ds_read_b128 v[194:197], v247 offset:32768
	v_mfma_f32_16x16x32_bf16 v[32:35], v[214:217], v[132:135], v[32:35]
	ds_read_b128 v[198:201], v248 offset:32768
	v_mfma_f32_16x16x32_bf16 v[36:39], v[222:225], v[132:135], v[36:39]
	ds_read_b128 v[202:205], v247 offset:34816
	v_mfma_f32_16x16x32_bf16 v[36:39], v[218:221], v[128:131], v[36:39]
	ds_read_b128 v[206:209], v248 offset:34816
	v_mfma_f32_16x16x32_bf16 v[44:47], v[218:221], v[136:139], v[44:47]
	s_add_i32 m0, s35, 0x8000
	v_mfma_f32_16x16x32_bf16 v[44:47], v[222:225], v[140:143], v[44:47]
	global_load_lds_dwordx4 v249, s[30:31]
	v_mfma_f32_16x16x32_bf16 v[40:43], v[214:217], v[140:143], v[40:43]
	s_add_i32 m0, s35, 0xa000
	v_mfma_f32_16x16x32_bf16 v[40:43], v[210:213], v[136:139], v[40:43]
	global_load_lds_dwordx4 v250, s[30:31]
	v_mfma_f32_16x16x32_bf16 v[48:51], v[210:213], v[144:147], v[48:51]
	s_add_i32 m0, s35, 0x1c000
	v_mfma_f32_16x16x32_bf16 v[48:51], v[214:217], v[148:151], v[48:51]
	global_load_lds_dwordx4 v251, s[58:59]
	v_mfma_f32_16x16x32_bf16 v[52:55], v[222:225], v[148:151], v[52:55]
	s_add_i32 m0, s35, 0x1e000
	v_mfma_f32_16x16x32_bf16 v[52:55], v[218:221], v[144:147], v[52:55]
	global_load_lds_dwordx4 v252, s[58:59]
	v_mfma_f32_16x16x32_bf16 v[60:63], v[218:221], v[152:155], v[60:63]
	ds_read_b128 v[160:163], v245 offset:49152
	v_mfma_f32_16x16x32_bf16 v[60:63], v[222:225], v[156:159], v[60:63]
	ds_read_b128 v[164:167], v246 offset:49152
	v_mfma_f32_16x16x32_bf16 v[56:59], v[214:217], v[156:159], v[56:59]
	ds_read_b128 v[168:171], v245 offset:51200
	v_mfma_f32_16x16x32_bf16 v[56:59], v[210:213], v[152:155], v[56:59]
	ds_read_b128 v[172:175], v246 offset:51200
	s_waitcnt lgkmcnt(4)
	v_mfma_f32_16x16x32_bf16 v[0:3], v[194:197], v[128:131], v[0:3]
	ds_read_b128 v[176:179], v245 offset:53248
	v_mfma_f32_16x16x32_bf16 v[0:3], v[198:201], v[132:135], v[0:3]
	ds_read_b128 v[180:183], v246 offset:53248
	v_mfma_f32_16x16x32_bf16 v[4:7], v[206:209], v[132:135], v[4:7]
	ds_read_b128 v[186:189], v245 offset:55296
	v_mfma_f32_16x16x32_bf16 v[4:7], v[202:205], v[128:131], v[4:7]
	ds_read_b128 v[190:193], v246 offset:55296
	v_mfma_f32_16x16x32_bf16 v[12:15], v[202:205], v[136:139], v[12:15]
	v_mfma_f32_16x16x32_bf16 v[12:15], v[206:209], v[140:143], v[12:15]
	v_mfma_f32_16x16x32_bf16 v[8:11], v[198:201], v[140:143], v[8:11]
	v_mfma_f32_16x16x32_bf16 v[8:11], v[194:197], v[136:139], v[8:11]
	v_mfma_f32_16x16x32_bf16 v[16:19], v[194:197], v[144:147], v[16:19]
	v_mfma_f32_16x16x32_bf16 v[16:19], v[198:201], v[148:151], v[16:19]
	v_mfma_f32_16x16x32_bf16 v[20:23], v[206:209], v[148:151], v[20:23]
	v_mfma_f32_16x16x32_bf16 v[20:23], v[202:205], v[144:147], v[20:23]
	v_mfma_f32_16x16x32_bf16 v[28:31], v[202:205], v[152:155], v[28:31]
	v_mfma_f32_16x16x32_bf16 v[28:31], v[206:209], v[156:159], v[28:31]
	v_mfma_f32_16x16x32_bf16 v[24:27], v[198:201], v[156:159], v[24:27]
	v_mfma_f32_16x16x32_bf16 v[24:27], v[194:197], v[152:155], v[24:27]
	s_waitcnt vmcnt(8)
	s_waitcnt lgkmcnt(0)
	s_barrier
	v_mfma_f32_16x16x32_bf16 v[64:67], v[194:197], v[160:163], v[64:67]
	s_add_i32 m0, s35, 0xc000
	v_mfma_f32_16x16x32_bf16 v[64:67], v[198:201], v[164:167], v[64:67]
	global_load_lds_dwordx4 v249, s[56:57]
	v_mfma_f32_16x16x32_bf16 v[68:71], v[206:209], v[164:167], v[68:71]
	s_add_i32 m0, s35, 0xe000
	v_mfma_f32_16x16x32_bf16 v[68:71], v[202:205], v[160:163], v[68:71]
	global_load_lds_dwordx4 v250, s[56:57]
	v_mfma_f32_16x16x32_bf16 v[76:79], v[202:205], v[168:171], v[76:79]
	s_add_i32 m0, s35, 0x18000
	v_mfma_f32_16x16x32_bf16 v[76:79], v[206:209], v[172:175], v[76:79]
	global_load_lds_dwordx4 v251, s[32:33]
	v_mfma_f32_16x16x32_bf16 v[72:75], v[198:201], v[172:175], v[72:75]
	s_add_i32 m0, s35, 0x1a000
	v_mfma_f32_16x16x32_bf16 v[72:75], v[194:197], v[168:171], v[72:75]
	global_load_lds_dwordx4 v252, s[32:33]
	v_mfma_f32_16x16x32_bf16 v[80:83], v[194:197], v[176:179], v[80:83]
	ds_read_b128 v[128:131], v245 offset:0
	v_mfma_f32_16x16x32_bf16 v[80:83], v[198:201], v[180:183], v[80:83]
	ds_read_b128 v[132:135], v246 offset:0
	v_mfma_f32_16x16x32_bf16 v[84:87], v[206:209], v[180:183], v[84:87]
	ds_read_b128 v[136:139], v245 offset:2048
	v_mfma_f32_16x16x32_bf16 v[84:87], v[202:205], v[176:179], v[84:87]
	ds_read_b128 v[140:143], v246 offset:2048
	v_mfma_f32_16x16x32_bf16 v[92:95], v[202:205], v[186:189], v[92:95]
	ds_read_b128 v[144:147], v245 offset:4096
	v_mfma_f32_16x16x32_bf16 v[92:95], v[206:209], v[190:193], v[92:95]
	ds_read_b128 v[148:151], v246 offset:4096
	v_mfma_f32_16x16x32_bf16 v[88:91], v[198:201], v[190:193], v[88:91]
	ds_read_b128 v[152:155], v245 offset:6144
	v_mfma_f32_16x16x32_bf16 v[88:91], v[194:197], v[186:189], v[88:91]
	ds_read_b128 v[156:159], v246 offset:6144
	v_mfma_f32_16x16x32_bf16 v[96:99], v[210:213], v[160:163], v[96:99]
	ds_read_b128 v[194:197], v247 offset:0
	v_mfma_f32_16x16x32_bf16 v[96:99], v[214:217], v[164:167], v[96:99]
	ds_read_b128 v[198:201], v248 offset:0
	v_mfma_f32_16x16x32_bf16 v[100:103], v[222:225], v[164:167], v[100:103]
	ds_read_b128 v[202:205], v247 offset:2048
	v_mfma_f32_16x16x32_bf16 v[100:103], v[218:221], v[160:163], v[100:103]
	ds_read_b128 v[206:209], v248 offset:2048
	v_mfma_f32_16x16x32_bf16 v[108:111], v[218:221], v[168:171], v[108:111]
	s_add_u32 s30, s30, s4
	s_addc_u32 s31, s31, s5
	v_mfma_f32_16x16x32_bf16 v[108:111], v[222:225], v[172:175], v[108:111]
	s_add_u32 s56, s56, s4
	s_addc_u32 s57, s57, s5
	v_mfma_f32_16x16x32_bf16 v[104:107], v[214:217], v[172:175], v[104:107]
	s_add_u32 s32, s32, s4
	s_addc_u32 s33, s33, s5
	v_mfma_f32_16x16x32_bf16 v[104:107], v[210:213], v[168:171], v[104:107]
	s_add_u32 s58, s58, s4
	s_addc_u32 s59, s59, s5
	v_mfma_f32_16x16x32_bf16 v[112:115], v[210:213], v[176:179], v[112:115]
	v_mfma_f32_16x16x32_bf16 v[112:115], v[214:217], v[180:183], v[112:115]
	v_mfma_f32_16x16x32_bf16 v[116:119], v[222:225], v[180:183], v[116:119]
	v_mfma_f32_16x16x32_bf16 v[116:119], v[218:221], v[176:179], v[116:119]
	v_mfma_f32_16x16x32_bf16 v[124:127], v[218:221], v[186:189], v[124:127]
	v_mfma_f32_16x16x32_bf16 v[124:127], v[222:225], v[190:193], v[124:127]
	v_mfma_f32_16x16x32_bf16 v[120:123], v[214:217], v[190:193], v[120:123]
	v_mfma_f32_16x16x32_bf16 v[120:123], v[210:213], v[186:189], v[120:123]
	s_add_i32 s34, s34, -1
	s_cmp_lg_u32 s34, 1
	s_cbranch_scc1 .Lp6_nosw0
	s_add_u32 s45, s16, 1
	s_and_b32 s40, s45, 1
	s_lshl_b32 s4, s40, 8
	s_sub_u32 s4, 128, s4
	s_sub_u32 s5, 0, s40
	s_mul_i32 s8, s40, 11136
	s_add_u32 s30, s26, s8
	s_addc_u32 s31, s27, 0
	s_add_u32 s32, s28, s8
	s_addc_u32 s33, s29, 0
	s_add_u32 s56, s30, 0x160000
	s_addc_u32 s57, s31, 0
	s_add_u32 s58, s32, 0x160000
	s_addc_u32 s59, s33, 0

; #define PG8_STAGE(bufoff, gbase, voff) do { _Pragma("unroll") for (int _i = 0; _i < 2; ++_i) \
;         __builtin_amdgcn_global_load_lds((const unsigned*)((const char*)(gbase) + (voff)[_i]), (PG8_LAS unsigned*)(lds + (bufoff) + ldsw + _i * 8192), 16, 0, 0); } while (0)
; #define PG8_LDA(dst, b, h) do { _Pragma("unroll") for (int m = 0; m < 4; ++m) _Pragma("unroll") for (int k = 0; k < 2; ++k) dst[m][k] = *(const PG8_LAS bf16x8*)(lds + PG8_SA(b, h) + aoff + m * 2048 + k * 1024); } while (0)
; #define PG8_LDB(dst, b, h) do { _Pragma("unroll") for (int n = 0; n < 2; ++n) _Pragma("unroll") for (int k = 0; k < 2; ++k) dst[n][k] = *(const PG8_LAS bf16x8*)(lds + PG8_SB(b, h) + boff + n * 2048 + k * 1024); } while (0)
; #define PG8_MMA(ai, bj, At, Bt) do { __builtin_amdgcn_s_setprio(1); _Pragma("unroll") for (int m = 0; m < 4; ++m) _Pragma("unroll") for (int n = 0; n < 2; ++n) _Pragma("unroll") for (int k = 0; k < 2; ++k) \
;         acc[ai][bj][m][n] = __builtin_amdgcn_mfma_f32_16x16x32_bf16(Bt[n][k], At[m][k], acc[ai][bj][m][n], 0, 0, 0); __builtin_amdgcn_s_setprio(0); } while (0)
; #define PG8_WAIT_V(n) asm volatile("s_waitcnt vmcnt(" #n ")" ::: "memory")
; template <class Epi, class Sched, bool ALIGN_EPI = false, bool SP2 = false>
; __device__ __forceinline__ void gemm_phase(PG8_LAS unsigned char* lds, const Gemm g, const Sched& S, const Epi& E) {
;     ...
;             PG8_LDB(B0, 0, 0); PG8_LDB(B1, 0, 1); PG8_SCHED; PG8_LDA(At, 0, 0); PG8_STAGE(PG8_SA(1, 1), a1 + hstep, voffA);
;             PG8_WAIT_V(8); PG8_WAIT_L(0); PG8_BAR; PG8_MMA(0, 0, At, B0); PG8_MMA(0, 1, At, B1); PG8_BAR; PG8_SCHED;
;             PG8_LDA(At, 0, 1); PG8_STAGE(PG8_SB(0, 0), b2, voffB); PG8_STAGE(PG8_SB(0, 1), b2 + hstep, voffB); PG8_STAGE(PG8_SA(0, 0), a2, voffA);
;             PG8_WAIT_V(8); PG8_WAIT_L(0); PG8_BAR; PG8_MMA(1, 0, At, B0); PG8_MMA(1, 1, At, B1); PG8_BAR; PG8_SCHED;
;             PG8_LDB(B0, 1, 0); PG8_LDB(B1, 1, 1); PG8_SCHED; PG8_LDA(At, 1, 0); PG8_STAGE(PG8_SA(0, 1), a2 + hstep, voffA);
;             PG8_WAIT_V(8); PG8_WAIT_L(0); PG8_BAR; PG8_MMA(0, 0, At, B0); PG8_MMA(0, 1, At, B1); PG8_BAR; PG8_SCHED;
;             PG8_LDA(At, 1, 1); PG8_STAGE(PG8_SB(1, 0), b3, voffB); PG8_STAGE(PG8_SB(1, 1), b3 + hstep, voffB); PG8_STAGE(PG8_SA(1, 0), a3, voffA);
;             PG8_WAIT_V(8); PG8_WAIT_L(0); PG8_BAR; PG8_MMA(1, 0, At, B0); PG8_MMA(1, 1, At, B1); PG8_BAR; PG8_SCHED;
.Lp6_kloop1:
	s_waitcnt vmcnt(8)
	s_waitcnt lgkmcnt(0)
	s_barrier
	v_mfma_f32_16x16x32_bf16 v[0:3], v[194:197], v[128:131], v[0:3]
	ds_read_b128 v[210:213], v247 offset:16384
	v_mfma_f32_16x16x32_bf16 v[0:3], v[198:201], v[132:135], v[0:3]
	ds_read_b128 v[214:217], v248 offset:16384
	v_mfma_f32_16x16x32_bf16 v[4:7], v[206:209], v[132:135], v[4:7]
	ds_read_b128 v[218:221], v247 offset:18432
	v_mfma_f32_16x16x32_bf16 v[4:7], v[202:205], v[128:131], v[4:7]
	ds_read_b128 v[222:225], v248 offset:18432
	v_mfma_f32_16x16x32_bf16 v[12:15], v[202:205], v[136:139], v[12:15]
	ds_read_b128 v[160:163], v245 offset:16384
	v_mfma_f32_16x16x32_bf16 v[12:15], v[206:209], v[140:143], v[12:15]
	ds_read_b128 v[164:167], v246 offset:16384
	v_mfma_f32_16x16x32_bf16 v[8:11], v[198:201], v[140:143], v[8:11]
	ds_read_b128 v[168:171], v245 offset:18432
	v_mfma_f32_16x16x32_bf16 v[8:11], v[194:197], v[136:139], v[8:11]
	ds_read_b128 v[172:175], v246 offset:18432
	v_mfma_f32_16x16x32_bf16 v[16:19], v[194:197], v[144:147], v[16:19]
	ds_read_b128 v[176:179], v245 offset:20480
	v_mfma_f32_16x16x32_bf16 v[16:19], v[198:201], v[148:151], v[16:19]
	ds_read_b128 v[180:183], v246 offset:20480
	v_mfma_f32_16x16x32_bf16 v[20:23], v[206:209], v[148:151], v[20:23]
	ds_read_b128 v[186:189], v245 offset:22528
	v_mfma_f32_16x16x32_bf16 v[20:23], v[202:205], v[144:147], v[20:23]
	ds_read_b128 v[190:193], v246 offset:22528
	v_mfma_f32_16x16x32_bf16 v[28:31], v[202:205], v[152:155], v[28:31]
	v_mfma_f32_16x16x32_bf16 v[28:31], v[206:209], v[156:159], v[28:31]
	v_mfma_f32_16x16x32_bf16 v[24:27], v[198:201], v[156:159], v[24:27]
	v_mfma_f32_16x16x32_bf16 v[24:27], v[194:197], v[152:155], v[24:27]
	s_waitcnt lgkmcnt(8)
	v_mfma_f32_16x16x32_bf16 v[32:35], v[210:213], v[128:131], v[32:35]
	v_mfma_f32_16x16x32_bf16 v[32:35], v[214:217], v[132:135], v[32:35]
	s_add_i32 m0, s35, 0x0
	v_mfma_f32_16x16x32_bf16 v[36:39], v[222:225], v[132:135], v[36:39]
	global_load_lds_dwordx4 v249, s[30:31]
	v_mfma_f32_16x16x32_bf16 v[36:39], v[218:221], v[128:131], v[36:39]
	v_mfma_f32_16x16x32_bf16 v[44:47], v[218:221], v[136:139], v[44:47]
	s_add_i32 m0, s35, 0x2000
	v_mfma_f32_16x16x32_bf16 v[44:47], v[222:225], v[140:143], v[44:47]
	global_load_lds_dwordx4 v250, s[30:31]
	v_mfma_f32_16x16x32_bf16 v[40:43], v[214:217], v[140:143], v[40:43]
	v_mfma_f32_16x16x32_bf16 v[40:43], v[210:213], v[136:139], v[40:43]
	s_add_i32 m0, s35, 0x10000
	v_mfma_f32_16x16x32_bf16 v[48:51], v[210:213], v[144:147], v[48:51]
	global_load_lds_dwordx4 v251, s[32:33]
	v_mfma_f32_16x16x32_bf16 v[48:51], v[214:217], v[148:151], v[48:51]
	v_mfma_f32_16x16x32_bf16 v[52:55], v[222:225], v[148:151], v[52:55]
	s_add_i32 m0, s35, 0x12000
	v_mfma_f32_16x16x32_bf16 v[52:55], v[218:221], v[144:147], v[52:55]
	global_load_lds_dwordx4 v252, s[32:33]
	v_mfma_f32_16x16x32_bf16 v[60:63], v[218:221], v[152:155], v[60:63]
	v_mfma_f32_16x16x32_bf16 v[60:63], v[222:225], v[156:159], v[60:63]
	v_mfma_f32_16x16x32_bf16 v[56:59], v[214:217], v[156:159], v[56:59]
	v_mfma_f32_16x16x32_bf16 v[56:59], v[210:213], v[152:155], v[56:59]
	s_waitcnt vmcnt(8)
	s_waitcnt lgkmcnt(0)
	s_barrier
	v_mfma_f32_16x16x32_bf16 v[96:99], v[210:213], v[160:163], v[96:99]
	ds_read_b128 v[128:131], v245 offset:32768
	v_mfma_f32_16x16x32_bf16 v[96:99], v[214:217], v[164:167], v[96:99]
	ds_read_b128 v[132:135], v246 offset:32768
	v_mfma_f32_16x16x32_bf16 v[100:103], v[222:225], v[164:167], v[100:103]
	ds_read_b128 v[136:139], v245 offset:34816
	v_mfma_f32_16x16x32_bf16 v[100:103], v[218:221], v[160:163], v[100:103]
	ds_read_b128 v[140:143], v246 offset:34816
	v_mfma_f32_16x16x32_bf16 v[108:111], v[218:221], v[168:171], v[108:111]
	ds_read_b128 v[144:147], v245 offset:36864
	v_mfma_f32_16x16x32_bf16 v[108:111], v[222:225], v[172:175], v[108:111]
	ds_read_b128 v[148:151], v246 offset:36864
	v_mfma_f32_16x16x32_bf16 v[104:107], v[214:217], v[172:175], v[104:107]
	ds_read_b128 v[152:155], v245 offset:38912
	v_mfma_f32_16x16x32_bf16 v[104:107], v[210:213], v[168:171], v[104:107]
	ds_read_b128 v[156:159], v246 offset:38912
	v_mfma_f32_16x16x32_bf16 v[112:115], v[210:213], v[176:179], v[112:115]
	v_mfma_f32_16x16x32_bf16 v[112:115], v[214:217], v[180:183], v[112:115]
	v_mfma_f32_16x16x32_bf16 v[116:119], v[222:225], v[180:183], v[116:119]
	v_mfma_f32_16x16x32_bf16 v[116:119], v[218:221], v[176:179], v[116:119]
	v_mfma_f32_16x16x32_bf16 v[124:127], v[218:221], v[186:189], v[124:127]
	v_mfma_f32_16x16x32_bf16 v[124:127], v[222:225], v[190:193], v[124:127]
	v_mfma_f32_16x16x32_bf16 v[120:123], v[214:217], v[190:193], v[120:123]
	v_mfma_f32_16x16x32_bf16 v[120:123], v[210:213], v[186:189], v[120:123]
	v_mfma_f32_16x16x32_bf16 v[64:67], v[194:197], v[160:163], v[64:67]
	ds_read_b128 v[210:213], v247 offset:49152
	v_mfma_f32_16x16x32_bf16 v[64:67], v[198:201], v[164:167], v[64:67]
	ds_read_b128 v[214:217], v248 offset:49152
	v_mfma_f32_16x16x32_bf16 v[68:71], v[206:209], v[164:167], v[68:71]
	ds_read_b128 v[218:221], v247 offset:51200
	v_mfma_f32_16x16x32_bf16 v[68:71], v[202:205], v[160:163], v[68:71]
	ds_read_b128 v[222:225], v248 offset:51200
	v_mfma_f32_16x16x32_bf16 v[76:79], v[202:205], v[168:171], v[76:79]
	s_add_i32 m0, s35, 0x4000
	v_mfma_f32_16x16x32_bf16 v[76:79], v[206:209], v[172:175], v[76:79]
	global_load_lds_dwordx4 v249, s[56:57]
	v_mfma_f32_16x16x32_bf16 v[72:75], v[198:201], v[172:175], v[72:75]
	s_add_i32 m0, s35, 0x6000
	v_mfma_f32_16x16x32_bf16 v[72:75], v[194:197], v[168:171], v[72:75]
	global_load_lds_dwordx4 v250, s[56:57]
	v_mfma_f32_16x16x32_bf16 v[80:83], v[194:197], v[176:179], v[80:83]
	s_add_i32 m0, s35, 0x14000
	v_mfma_f32_16x16x32_bf16 v[80:83], v[198:201], v[180:183], v[80:83]
	global_load_lds_dwordx4 v251, s[58:59]
	v_mfma_f32_16x16x32_bf16 v[84:87], v[206:209], v[180:183], v[84:87]
	s_add_i32 m0, s35, 0x16000
	v_mfma_f32_16x16x32_bf16 v[84:87], v[202:205], v[176:179], v[84:87]
	global_load_lds_dwordx4 v252, s[58:59]
	v_mfma_f32_16x16x32_bf16 v[92:95], v[202:205], v[186:189], v[92:95]
	s_add_u32 s30, s30, s4
	s_addc_u32 s31, s31, s5
	v_mfma_f32_16x16x32_bf16 v[92:95], v[206:209], v[190:193], v[92:95]
	s_add_u32 s56, s56, s4
	s_addc_u32 s57, s57, s5
	v_mfma_f32_16x16x32_bf16 v[88:91], v[198:201], v[190:193], v[88:91]
	s_add_u32 s32, s32, s4
	s_addc_u32 s33, s33, s5
	v_mfma_f32_16x16x32_bf16 v[88:91], v[194:197], v[186:189], v[88:91]
	s_add_u32 s58, s58, s4
	s_addc_u32 s59, s59, s5
	s_waitcnt vmcnt(8)
	s_waitcnt lgkmcnt(0)
	s_barrier
; #define PG8_STAGE(bufoff, gbase, voff) do { _Pragma("unroll") for (int _i = 0; _i < 2; ++_i) \
;         __builtin_amdgcn_global_load_lds((const unsigned*)((const char*)(gbase) + (voff)[_i]), (PG8_LAS unsigned*)(lds + (bufoff) + ldsw + _i * 8192), 16, 0, 0); } while (0)
; #define PG8_LDA(dst, b, h) do { _Pragma("unroll") for (int m = 0; m < 4; ++m) _Pragma("unroll") for (int k = 0; k < 2; ++k) dst[m][k] = *(const PG8_LAS bf16x8*)(lds + PG8_SA(b, h) + aoff + m * 2048 + k * 1024); } while (0)
; #define PG8_LDB(dst, b, h) do { _Pragma("unroll") for (int n = 0; n < 2; ++n) _Pragma("unroll") for (int k = 0; k < 2; ++k) dst[n][k] = *(const PG8_LAS bf16x8*)(lds + PG8_SB(b, h) + boff + n * 2048 + k * 1024); } while (0)
; #define PG8_MMA(ai, bj, At, Bt) do { __builtin_amdgcn_s_setprio(1); _Pragma("unroll") for (int m = 0; m < 4; ++m) _Pragma("unroll") for (int n = 0; n < 2; ++n) _Pragma("unroll") for (int k = 0; k < 2; ++k) \
;         acc[ai][bj][m][n] = __builtin_amdgcn_mfma_f32_16x16x32_bf16(Bt[n][k], At[m][k], acc[ai][bj][m][n], 0, 0, 0); __builtin_amdgcn_s_setprio(0); } while (0)
; template <class Epi, class Sched, bool ALIGN_EPI = false, bool SP2 = false>
; __device__ __forceinline__ void gemm_phase(PG8_LAS unsigned char* lds, const Gemm g, const Sched& S, const Epi& E) {
;     ...
;         const bool has_next = S.next(ui + 1, nxt);
;         const char* nA = has_next ? (const char*)g.A + (size_t)nxt.pm * tstep : cA; const char* nB = has_next ? (const char*)g.Bt + (size_t)nxt.pn * tstep : cB;
;         for (int t = 0; t < nt; t += 2) {
;             const bool last = (t == nt - 2);
;             const char* a1 = cA + (size_t)(t + 1) * kstep;
;             const char* a2 = last ? nA : cA + (size_t)(t + 2) * kstep; const char* b2 = last ? nB : cB + (size_t)(t + 2) * kstep;
;             const char* a3 = a2 + kstep; const char* b3 = b2 + kstep;
;     ...
;             PG8_LDB(B0, 1, 0); PG8_LDB(B1, 1, 1); PG8_SCHED; PG8_LDA(At, 1, 0); PG8_STAGE(PG8_SA(0, 1), a2 + hstep, voffA);
;             PG8_WAIT_V(8); PG8_WAIT_L(0); PG8_BAR; PG8_MMA(0, 0, At, B0); PG8_MMA(0, 1, At, B1); PG8_BAR; PG8_SCHED;
;             PG8_LDA(At, 1, 1); PG8_STAGE(PG8_SB(1, 0), b3, voffB); PG8_STAGE(PG8_SB(1, 1), b3 + hstep, voffB); PG8_STAGE(PG8_SA(1, 0), a3, voffA);
;             PG8_WAIT_V(8); PG8_WAIT_L(0); PG8_BAR; PG8_MMA(1, 0, At, B0); PG8_MMA(1, 1, At, B1); PG8_BAR; PG8_SCHED;
	v_mfma_f32_16x16x32_bf16 v[32:35], v[210:213], v[128:131], v[32:35]
	ds_read_b128 v[194:197], v247 offset:32768
	v_mfma_f32_16x16x32_bf16 v[32:35], v[214:217], v[132:135], v[32:35]
	ds_read_b128 v[198:201], v248 offset:32768
	v_mfma_f32_16x16x32_bf16 v[36:39], v[222:225], v[132:135], v[36:39]
	ds_read_b128 v[202:205], v247 offset:34816
	v_mfma_f32_16x16x32_bf16 v[36:39], v[218:221], v[128:131], v[36:39]
	ds_read_b128 v[206:209], v248 offset:34816
	v_mfma_f32_16x16x32_bf16 v[44:47], v[218:221], v[136:139], v[44:47]
	ds_read_b128 v[160:163], v245 offset:49152
	v_mfma_f32_16x16x32_bf16 v[44:47], v[222:225], v[140:143], v[44:47]
	ds_read_b128 v[164:167], v246 offset:49152
	v_mfma_f32_16x16x32_bf16 v[40:43], v[214:217], v[140:143], v[40:43]
	ds_read_b128 v[168:171], v245 offset:51200
	v_mfma_f32_16x16x32_bf16 v[40:43], v[210:213], v[136:139], v[40:43]
	ds_read_b128 v[172:175], v246 offset:51200
	v_mfma_f32_16x16x32_bf16 v[48:51], v[210:213], v[144:147], v[48:51]
	ds_read_b128 v[176:179], v245 offset:53248
	v_mfma_f32_16x16x32_bf16 v[48:51], v[214:217], v[148:151], v[48:51]
	ds_read_b128 v[180:183], v246 offset:53248
	v_mfma_f32_16x16x32_bf16 v[52:55], v[222:225], v[148:151], v[52:55]
	ds_read_b128 v[186:189], v245 offset:55296
	v_mfma_f32_16x16x32_bf16 v[52:55], v[218:221], v[144:147], v[52:55]
	ds_read_b128 v[190:193], v246 offset:55296
	v_mfma_f32_16x16x32_bf16 v[60:63], v[218:221], v[152:155], v[60:63]
	v_mfma_f32_16x16x32_bf16 v[60:63], v[222:225], v[156:159], v[60:63]
	v_mfma_f32_16x16x32_bf16 v[56:59], v[214:217], v[156:159], v[56:59]
	v_mfma_f32_16x16x32_bf16 v[56:59], v[210:213], v[152:155], v[56:59]
	s_waitcnt lgkmcnt(8)
	v_mfma_f32_16x16x32_bf16 v[0:3], v[194:197], v[128:131], v[0:3]
	v_mfma_f32_16x16x32_bf16 v[0:3], v[198:201], v[132:135], v[0:3]
	s_add_i32 m0, s35, 0x8000
	v_mfma_f32_16x16x32_bf16 v[4:7], v[206:209], v[132:135], v[4:7]
	global_load_lds_dwordx4 v249, s[30:31]
	v_mfma_f32_16x16x32_bf16 v[4:7], v[202:205], v[128:131], v[4:7]
	v_mfma_f32_16x16x32_bf16 v[12:15], v[202:205], v[136:139], v[12:15]
	s_add_i32 m0, s35, 0xa000
	v_mfma_f32_16x16x32_bf16 v[12:15], v[206:209], v[140:143], v[12:15]
	global_load_lds_dwordx4 v250, s[30:31]
	v_mfma_f32_16x16x32_bf16 v[8:11], v[198:201], v[140:143], v[8:11]
	v_mfma_f32_16x16x32_bf16 v[8:11], v[194:197], v[136:139], v[8:11]
	s_add_i32 m0, s35, 0x1c000
	v_mfma_f32_16x16x32_bf16 v[16:19], v[194:197], v[144:147], v[16:19]
	global_load_lds_dwordx4 v251, s[58:59]
	v_mfma_f32_16x16x32_bf16 v[16:19], v[198:201], v[148:151], v[16:19]
	v_mfma_f32_16x16x32_bf16 v[20:23], v[206:209], v[148:151], v[20:23]
	s_add_i32 m0, s35, 0x1e000
	v_mfma_f32_16x16x32_bf16 v[20:23], v[202:205], v[144:147], v[20:23]
	global_load_lds_dwordx4 v252, s[58:59]
	v_mfma_f32_16x16x32_bf16 v[28:31], v[202:205], v[152:155], v[28:31]
	v_mfma_f32_16x16x32_bf16 v[28:31], v[206:209], v[156:159], v[28:31]
	v_mfma_f32_16x16x32_bf16 v[24:27], v[198:201], v[156:159], v[24:27]
	v_mfma_f32_16x16x32_bf16 v[24:27], v[194:197], v[152:155], v[24:27]
	s_waitcnt vmcnt(8)
	s_waitcnt lgkmcnt(0)
	s_barrier
	v_mfma_f32_16x16x32_bf16 v[64:67], v[194:197], v[160:163], v[64:67]
	ds_read_b128 v[128:131], v245 offset:0
	v_mfma_f32_16x16x32_bf16 v[64:67], v[198:201], v[164:167], v[64:67]
	ds_read_b128 v[132:135], v246 offset:0
	v_mfma_f32_16x16x32_bf16 v[68:71], v[206:209], v[164:167], v[68:71]
	ds_read_b128 v[136:139], v245 offset:2048
	v_mfma_f32_16x16x32_bf16 v[68:71], v[202:205], v[160:163], v[68:71]
	ds_read_b128 v[140:143], v246 offset:2048
	v_mfma_f32_16x16x32_bf16 v[76:79], v[202:205], v[168:171], v[76:79]
	ds_read_b128 v[144:147], v245 offset:4096
	v_mfma_f32_16x16x32_bf16 v[76:79], v[206:209], v[172:175], v[76:79]
	ds_read_b128 v[148:151], v246 offset:4096
	v_mfma_f32_16x16x32_bf16 v[72:75], v[198:201], v[172:175], v[72:75]
	ds_read_b128 v[152:155], v245 offset:6144
	v_mfma_f32_16x16x32_bf16 v[72:75], v[194:197], v[168:171], v[72:75]
	ds_read_b128 v[156:159], v246 offset:6144
	v_mfma_f32_16x16x32_bf16 v[80:83], v[194:197], v[176:179], v[80:83]
	v_mfma_f32_16x16x32_bf16 v[80:83], v[198:201], v[180:183], v[80:83]
	v_mfma_f32_16x16x32_bf16 v[84:87], v[206:209], v[180:183], v[84:87]
	v_mfma_f32_16x16x32_bf16 v[84:87], v[202:205], v[176:179], v[84:87]
	v_mfma_f32_16x16x32_bf16 v[92:95], v[202:205], v[186:189], v[92:95]
	v_mfma_f32_16x16x32_bf16 v[92:95], v[206:209], v[190:193], v[92:95]
	v_mfma_f32_16x16x32_bf16 v[88:91], v[198:201], v[190:193], v[88:91]
	v_mfma_f32_16x16x32_bf16 v[88:91], v[194:197], v[186:189], v[88:91]
	v_mfma_f32_16x16x32_bf16 v[96:99], v[210:213], v[160:163], v[96:99]
	ds_read_b128 v[194:197], v247 offset:0
	v_mfma_f32_16x16x32_bf16 v[96:99], v[214:217], v[164:167], v[96:99]
	ds_read_b128 v[198:201], v248 offset:0
	v_mfma_f32_16x16x32_bf16 v[100:103], v[222:225], v[164:167], v[100:103]
	ds_read_b128 v[202:205], v247 offset:2048
	v_mfma_f32_16x16x32_bf16 v[100:103], v[218:221], v[160:163], v[100:103]
	ds_read_b128 v[206:209], v248 offset:2048
	v_mfma_f32_16x16x32_bf16 v[108:111], v[218:221], v[168:171], v[108:111]
	s_add_i32 m0, s35, 0xc000
	v_mfma_f32_16x16x32_bf16 v[108:111], v[222:225], v[172:175], v[108:111]
	global_load_lds_dwordx4 v249, s[56:57]
	v_mfma_f32_16x16x32_bf16 v[104:107], v[214:217], v[172:175], v[104:107]
	s_add_i32 m0, s35, 0xe000
	v_mfma_f32_16x16x32_bf16 v[104:107], v[210:213], v[168:171], v[104:107]
	global_load_lds_dwordx4 v250, s[56:57]
	v_mfma_f32_16x16x32_bf16 v[112:115], v[210:213], v[176:179], v[112:115]
	s_add_i32 m0, s35, 0x18000
	v_mfma_f32_16x16x32_bf16 v[112:115], v[214:217], v[180:183], v[112:115]
	global_load_lds_dwordx4 v251, s[32:33]
	v_mfma_f32_16x16x32_bf16 v[116:119], v[222:225], v[180:183], v[116:119]
	s_add_i32 m0, s35, 0x1a000
	v_mfma_f32_16x16x32_bf16 v[116:119], v[218:221], v[176:179], v[116:119]
	global_load_lds_dwordx4 v252, s[32:33]
	v_mfma_f32_16x16x32_bf16 v[124:127], v[218:221], v[186:189], v[124:127]
	s_add_u32 s30, s30, s4
	s_addc_u32 s31, s31, s5
	v_mfma_f32_16x16x32_bf16 v[124:127], v[222:225], v[190:193], v[124:127]
	s_add_u32 s56, s56, s4
	s_addc_u32 s57, s57, s5
	v_mfma_f32_16x16x32_bf16 v[120:123], v[214:217], v[190:193], v[120:123]
	s_add_u32 s32, s32, s4
	s_addc_u32 s33, s33, s5
	v_mfma_f32_16x16x32_bf16 v[120:123], v[210:213], v[186:189], v[120:123]
	s_add_u32 s58, s58, s4
	s_addc_u32 s59, s59, s5
	s_add_i32 s34, s34, -1
	s_cmp_lg_u32 s34, 1
	s_cbranch_scc1 .Lp6_nosw1
	s_add_u32 s45, s16, 1
	s_and_b32 s40, s45, 1
	s_lshl_b32 s4, s40, 8
	s_sub_u32 s4, 128, s4
	s_sub_u32 s5, 0, s40
	s_mul_i32 s8, s40, 11136
	s_add_u32 s30, s26, s8
	s_addc_u32 s31, s27, 0
	s_add_u32 s32, s28, s8
	s_addc_u32 s33, s29, 0
	s_add_u32 s56, s30, 0x160000
	s_addc_u32 s57, s31, 0
	s_add_u32 s58, s32, 0x160000
	s_addc_u32 s59, s33, 0

; #define PG8_STAGE(bufoff, gbase, voff) do { _Pragma("unroll") for (int _i = 0; _i < 2; ++_i) \
;         __builtin_amdgcn_global_load_lds((const unsigned*)((const char*)(gbase) + (voff)[_i]), (PG8_LAS unsigned*)(lds + (bufoff) + ldsw + _i * 8192), 16, 0, 0); } while (0)
; #define PG8_LDA(dst, b, h) do { _Pragma("unroll") for (int m = 0; m < 4; ++m) _Pragma("unroll") for (int k = 0; k < 2; ++k) dst[m][k] = *(const PG8_LAS bf16x8*)(lds + PG8_SA(b, h) + aoff + m * 2048 + k * 1024); } while (0)
; #define PG8_LDB(dst, b, h) do { _Pragma("unroll") for (int n = 0; n < 2; ++n) _Pragma("unroll") for (int k = 0; k < 2; ++k) dst[n][k] = *(const PG8_LAS bf16x8*)(lds + PG8_SB(b, h) + boff + n * 2048 + k * 1024); } while (0)
; #define PG8_MMA(ai, bj, At, Bt) do { __builtin_amdgcn_s_setprio(1); _Pragma("unroll") for (int m = 0; m < 4; ++m) _Pragma("unroll") for (int n = 0; n < 2; ++n) _Pragma("unroll") for (int k = 0; k < 2; ++k) \
;         acc[ai][bj][m][n] = __builtin_amdgcn_mfma_f32_16x16x32_bf16(Bt[n][k], At[m][k], acc[ai][bj][m][n], 0, 0, 0); __builtin_amdgcn_s_setprio(0); } while (0)
; #define PG8_WAIT_V(n) asm volatile("s_waitcnt vmcnt(" #n ")" ::: "memory")
; #define PG8_WAIT_L(n) asm volatile("s_waitcnt lgkmcnt(" #n ")" ::: "memory")
; #define PG8_BAR __builtin_amdgcn_s_barrier()
; #define PG8_SCHED __builtin_amdgcn_sched_barrier(0)
; template <class Epi, class Sched, bool ALIGN_EPI = false, bool SP2 = false>
; __device__ __forceinline__ void gemm_phase(PG8_LAS unsigned char* lds, const Gemm g, const Sched& S, const Epi& E) {
;     ...
;             PG8_LDB(B0, 0, 0); PG8_LDB(B1, 0, 1); PG8_SCHED; PG8_LDA(At, 0, 0); PG8_STAGE(PG8_SA(1, 1), a1 + hstep, voffA);
;             PG8_WAIT_V(8); PG8_WAIT_L(0); PG8_BAR; PG8_MMA(0, 0, At, B0); PG8_MMA(0, 1, At, B1); PG8_BAR; PG8_SCHED;
;             PG8_LDA(At, 0, 1); PG8_STAGE(PG8_SB(0, 0), b2, voffB); PG8_STAGE(PG8_SB(0, 1), b2 + hstep, voffB); PG8_STAGE(PG8_SA(0, 0), a2, voffA);
;             PG8_WAIT_V(8); PG8_WAIT_L(0); PG8_BAR; PG8_MMA(1, 0, At, B0); PG8_MMA(1, 1, At, B1); PG8_BAR; PG8_SCHED;
.LBB0_864:
	ds_read_b128 v[104:107], v222
	ds_read_b128 v[108:111], v222 offset:1024
	ds_read_b128 v[124:127], v222 offset:2048
	ds_read_b128 v[136:139], v222 offset:3072
	ds_read_b128 v[144:147], v223
	ds_read_b128 v[148:151], v223 offset:1024
	ds_read_b128 v[152:155], v223 offset:2048
	ds_read_b128 v[156:159], v223 offset:3072
	s_add_u32 s22, s20, 0x100
	s_addc_u32 s23, s21, 0
	s_cmpk_eq_i32 s47, 0x54
	s_cselect_b32 s27, s7, s23
	s_cselect_b32 s26, s6, s22
	s_cselect_b32 s25, s19, s46
	s_cselect_b32 s24, s18, s45
	v_lshl_add_u64 v[210:211], s[20:21], 0, v[194:195]
	s_add_i32 m0, s28, 0xc000
	ds_read_b128 v[160:163], v224
	ds_read_b128 v[164:167], v224 offset:1024
	ds_read_b128 v[168:171], v224 offset:2048
	ds_read_b128 v[172:175], v224 offset:3072
	ds_read_b128 v[176:179], v224 offset:4096
	ds_read_b128 v[180:183], v224 offset:5120
	ds_read_b128 v[202:205], v224 offset:6144
	ds_read_b128 v[206:209], v224 offset:7168
	global_load_lds_dwordx4 v[210:211], off
	v_lshl_add_u64 v[210:211], s[20:21], 0, v[196:197]
	s_add_i32 m0, s28, 0xe000
	s_nop 0
	global_load_lds_dwordx4 v[210:211], off
	s_waitcnt vmcnt(8)
	s_waitcnt lgkmcnt(0)
	s_barrier
	s_setprio 1
	s_waitcnt lgkmcnt(0)
	v_mfma_f32_16x16x32_bf16 v[140:143], v[104:107], v[160:163], v[140:143]
	v_mfma_f32_16x16x32_bf16 v[140:143], v[108:111], v[164:167], v[140:143]
	v_mfma_f32_16x16x32_bf16 v[132:135], v[136:139], v[164:167], v[132:135]
	v_mfma_f32_16x16x32_bf16 v[132:135], v[124:127], v[160:163], v[132:135]
	v_mfma_f32_16x16x32_bf16 v[112:115], v[124:127], v[168:171], v[112:115]
	v_mfma_f32_16x16x32_bf16 v[112:115], v[136:139], v[172:175], v[112:115]
	v_mfma_f32_16x16x32_bf16 v[116:119], v[108:111], v[172:175], v[116:119]
	v_mfma_f32_16x16x32_bf16 v[116:119], v[104:107], v[168:171], v[116:119]
	v_mfma_f32_16x16x32_bf16 v[92:95], v[104:107], v[176:179], v[92:95]
	v_mfma_f32_16x16x32_bf16 v[92:95], v[108:111], v[180:183], v[92:95]
	v_mfma_f32_16x16x32_bf16 v[88:91], v[136:139], v[180:183], v[88:91]
	v_mfma_f32_16x16x32_bf16 v[88:91], v[124:127], v[176:179], v[88:91]
	v_mfma_f32_16x16x32_bf16 v[72:75], v[124:127], v[202:205], v[72:75]
	v_mfma_f32_16x16x32_bf16 v[72:75], v[136:139], v[206:209], v[72:75]
	v_mfma_f32_16x16x32_bf16 v[76:79], v[108:111], v[206:209], v[76:79]
	v_mfma_f32_16x16x32_bf16 v[76:79], v[104:107], v[202:205], v[76:79]
	s_setprio 0
	s_setprio 1
	v_mfma_f32_16x16x32_bf16 v[128:131], v[144:147], v[160:163], v[128:131]
	v_mfma_f32_16x16x32_bf16 v[128:131], v[148:151], v[164:167], v[128:131]
	v_mfma_f32_16x16x32_bf16 v[120:123], v[156:159], v[164:167], v[120:123]
	v_mfma_f32_16x16x32_bf16 v[120:123], v[152:155], v[160:163], v[120:123]
	v_mfma_f32_16x16x32_bf16 v[96:99], v[152:155], v[168:171], v[96:99]
	v_mfma_f32_16x16x32_bf16 v[96:99], v[156:159], v[172:175], v[96:99]
	v_mfma_f32_16x16x32_bf16 v[100:103], v[148:151], v[172:175], v[100:103]
	v_mfma_f32_16x16x32_bf16 v[100:103], v[144:147], v[168:171], v[100:103]
	v_mfma_f32_16x16x32_bf16 v[84:87], v[144:147], v[176:179], v[84:87]
	v_mfma_f32_16x16x32_bf16 v[84:87], v[148:151], v[180:183], v[84:87]
	v_mfma_f32_16x16x32_bf16 v[80:83], v[156:159], v[180:183], v[80:83]
	v_mfma_f32_16x16x32_bf16 v[80:83], v[152:155], v[176:179], v[80:83]
	v_mfma_f32_16x16x32_bf16 v[64:67], v[152:155], v[202:205], v[64:67]
	v_mfma_f32_16x16x32_bf16 v[64:67], v[156:159], v[206:209], v[64:67]
	v_mfma_f32_16x16x32_bf16 v[68:71], v[148:151], v[206:209], v[68:71]
	v_mfma_f32_16x16x32_bf16 v[68:71], v[144:147], v[202:205], v[68:71]
	s_setprio 0
	s_barrier
	s_add_i32 s20, s39, s3
	v_lshl_add_u64 v[210:211], s[24:25], 0, v[188:189]
	s_mov_b32 m0, s20
	ds_read_b128 v[160:163], v224 offset:16384
	ds_read_b128 v[164:167], v224 offset:17408
	ds_read_b128 v[168:171], v224 offset:18432
	ds_read_b128 v[172:175], v224 offset:19456
	ds_read_b128 v[176:179], v224 offset:20480
	ds_read_b128 v[180:183], v224 offset:21504
	ds_read_b128 v[202:205], v224 offset:22528
	ds_read_b128 v[206:209], v224 offset:23552
	global_load_lds_dwordx4 v[210:211], off
	s_add_i32 m0, s20, 0x2000
	s_add_u32 s20, s24, 0x160000
	v_lshl_add_u64 v[212:213], s[24:25], 0, v[192:193]
	s_addc_u32 s21, s25, 0
	s_add_i32 s48, s40, s3
	global_load_lds_dwordx4 v[212:213], off
	v_lshl_add_u64 v[214:215], s[20:21], 0, v[188:189]
	s_mov_b32 m0, s48
	v_lshl_add_u64 v[216:217], s[26:27], 0, v[190:191]
	global_load_lds_dwordx4 v[214:215], off
	v_lshl_add_u64 v[214:215], s[20:21], 0, v[192:193]
	s_add_i32 m0, s48, 0x2000
	s_nop 0
	global_load_lds_dwordx4 v[214:215], off
	v_lshl_add_u64 v[214:215], s[26:27], 0, v[186:187]
	s_mov_b32 m0, s28
	s_nop 0
	global_load_lds_dwordx4 v[214:215], off
	s_mov_b32 m0, s29
	s_nop 0
	global_load_lds_dwordx4 v[216:217], off
	s_waitcnt vmcnt(8)
	s_waitcnt lgkmcnt(0)
	s_barrier
; #define PG8_STAGE(bufoff, gbase, voff) do { _Pragma("unroll") for (int _i = 0; _i < 2; ++_i) \
;         __builtin_amdgcn_global_load_lds((const unsigned*)((const char*)(gbase) + (voff)[_i]), (PG8_LAS unsigned*)(lds + (bufoff) + ldsw + _i * 8192), 16, 0, 0); } while (0)
; #define PG8_LDA(dst, b, h) do { _Pragma("unroll") for (int m = 0; m < 4; ++m) _Pragma("unroll") for (int k = 0; k < 2; ++k) dst[m][k] = *(const PG8_LAS bf16x8*)(lds + PG8_SA(b, h) + aoff + m * 2048 + k * 1024); } while (0)
; #define PG8_LDB(dst, b, h) do { _Pragma("unroll") for (int n = 0; n < 2; ++n) _Pragma("unroll") for (int k = 0; k < 2; ++k) dst[n][k] = *(const PG8_LAS bf16x8*)(lds + PG8_SB(b, h) + boff + n * 2048 + k * 1024); } while (0)
; #define PG8_MMA(ai, bj, At, Bt) do { __builtin_amdgcn_s_setprio(1); _Pragma("unroll") for (int m = 0; m < 4; ++m) _Pragma("unroll") for (int n = 0; n < 2; ++n) _Pragma("unroll") for (int k = 0; k < 2; ++k) \
;         acc[ai][bj][m][n] = __builtin_amdgcn_mfma_f32_16x16x32_bf16(Bt[n][k], At[m][k], acc[ai][bj][m][n], 0, 0, 0); __builtin_amdgcn_s_setprio(0); } while (0)
; #define PG8_WAIT_V(n) asm volatile("s_waitcnt vmcnt(" #n ")" ::: "memory")
; #define PG8_WAIT_L(n) asm volatile("s_waitcnt lgkmcnt(" #n ")" ::: "memory")
; #define PG8_BAR __builtin_amdgcn_s_barrier()
; #define PG8_SCHED __builtin_amdgcn_sched_barrier(0)
; template <class Epi, class Sched, bool ALIGN_EPI = false, bool SP2 = false>
; __device__ __forceinline__ void gemm_phase(PG8_LAS unsigned char* lds, const Gemm g, const Sched& S, const Epi& E) {
;     ...
;             PG8_WAIT_V(8); PG8_WAIT_L(0); PG8_BAR; PG8_MMA(1, 0, At, B0); PG8_MMA(1, 1, At, B1); PG8_BAR; PG8_SCHED;
;             PG8_LDB(B0, 1, 0); PG8_LDB(B1, 1, 1); PG8_SCHED; PG8_LDA(At, 1, 0); PG8_STAGE(PG8_SA(0, 1), a2 + hstep, voffA);
;             PG8_WAIT_V(8); PG8_WAIT_L(0); PG8_BAR; PG8_MMA(0, 0, At, B0); PG8_MMA(0, 1, At, B1); PG8_BAR; PG8_SCHED;
	s_setprio 1
	s_waitcnt lgkmcnt(0)
	v_mfma_f32_16x16x32_bf16 v[60:63], v[104:107], v[160:163], v[60:63]
	v_mfma_f32_16x16x32_bf16 v[60:63], v[108:111], v[164:167], v[60:63]
	v_mfma_f32_16x16x32_bf16 v[56:59], v[136:139], v[164:167], v[56:59]
	v_mfma_f32_16x16x32_bf16 v[56:59], v[124:127], v[160:163], v[56:59]
	v_mfma_f32_16x16x32_bf16 v[40:43], v[124:127], v[168:171], v[40:43]
	v_mfma_f32_16x16x32_bf16 v[40:43], v[136:139], v[172:175], v[40:43]
	v_mfma_f32_16x16x32_bf16 v[44:47], v[108:111], v[172:175], v[44:47]
	v_mfma_f32_16x16x32_bf16 v[44:47], v[104:107], v[168:171], v[44:47]
	v_mfma_f32_16x16x32_bf16 v[28:31], v[104:107], v[176:179], v[28:31]
	v_mfma_f32_16x16x32_bf16 v[28:31], v[108:111], v[180:183], v[28:31]
	v_mfma_f32_16x16x32_bf16 v[24:27], v[136:139], v[180:183], v[24:27]
	v_mfma_f32_16x16x32_bf16 v[24:27], v[124:127], v[176:179], v[24:27]
	v_mfma_f32_16x16x32_bf16 v[8:11], v[124:127], v[202:205], v[8:11]
	v_mfma_f32_16x16x32_bf16 v[8:11], v[136:139], v[206:209], v[8:11]
	v_mfma_f32_16x16x32_bf16 v[12:15], v[108:111], v[206:209], v[12:15]
	v_mfma_f32_16x16x32_bf16 v[12:15], v[104:107], v[202:205], v[12:15]
	s_setprio 0
	s_setprio 1
	v_mfma_f32_16x16x32_bf16 v[52:55], v[144:147], v[160:163], v[52:55]
	v_mfma_f32_16x16x32_bf16 v[52:55], v[148:151], v[164:167], v[52:55]
	v_mfma_f32_16x16x32_bf16 v[48:51], v[156:159], v[164:167], v[48:51]
	v_mfma_f32_16x16x32_bf16 v[48:51], v[152:155], v[160:163], v[48:51]
	v_mfma_f32_16x16x32_bf16 v[32:35], v[152:155], v[168:171], v[32:35]
	v_mfma_f32_16x16x32_bf16 v[32:35], v[156:159], v[172:175], v[32:35]
	v_mfma_f32_16x16x32_bf16 v[36:39], v[148:151], v[172:175], v[36:39]
	v_mfma_f32_16x16x32_bf16 v[36:39], v[144:147], v[168:171], v[36:39]
	v_mfma_f32_16x16x32_bf16 v[20:23], v[144:147], v[176:179], v[20:23]
	v_mfma_f32_16x16x32_bf16 v[20:23], v[148:151], v[180:183], v[20:23]
	v_mfma_f32_16x16x32_bf16 v[16:19], v[156:159], v[180:183], v[16:19]
	v_mfma_f32_16x16x32_bf16 v[16:19], v[152:155], v[176:179], v[16:19]
	v_mfma_f32_16x16x32_bf16 v[0:3], v[152:155], v[202:205], v[0:3]
	v_mfma_f32_16x16x32_bf16 v[0:3], v[156:159], v[206:209], v[0:3]
	v_mfma_f32_16x16x32_bf16 v[4:7], v[148:151], v[206:209], v[4:7]
	v_mfma_f32_16x16x32_bf16 v[4:7], v[144:147], v[202:205], v[4:7]
	s_setprio 0
	s_barrier
	s_add_i32 s48, 0, 0x18000
	s_add_i32 s49, 0, 0x1c000
	v_add_u32_e32 v136, s48, v185
	v_add_u32_e32 v156, s49, v185
	ds_read_b128 v[104:107], v136
	ds_read_b128 v[108:111], v136 offset:1024
	ds_read_b128 v[124:127], v136 offset:2048
	ds_read_b128 v[136:139], v136 offset:3072
	ds_read_b128 v[144:147], v156
	ds_read_b128 v[148:151], v156 offset:1024
	ds_read_b128 v[152:155], v156 offset:2048
	ds_read_b128 v[156:159], v156 offset:3072
	s_add_u32 s20, s26, 0x160000
	s_addc_u32 s21, s27, 0
	s_mov_b32 m0, s30
	v_lshl_add_u64 v[218:219], s[20:21], 0, v[186:187]
	ds_read_b128 v[160:163], v224 offset:32768
	ds_read_b128 v[164:167], v224 offset:33792
	ds_read_b128 v[168:171], v224 offset:34816
	ds_read_b128 v[172:175], v224 offset:35840
	ds_read_b128 v[176:179], v224 offset:36864
	ds_read_b128 v[180:183], v224 offset:37888
	ds_read_b128 v[202:205], v224 offset:38912
	ds_read_b128 v[206:209], v224 offset:39936
	global_load_lds_dwordx4 v[218:219], off
	v_lshl_add_u64 v[218:219], s[20:21], 0, v[190:191]
	s_mov_b32 m0, s31
	s_nop 0
	global_load_lds_dwordx4 v[218:219], off
	s_waitcnt vmcnt(8)
	s_waitcnt lgkmcnt(0)
	s_barrier
	s_setprio 1
	s_waitcnt lgkmcnt(0)
	v_mfma_f32_16x16x32_bf16 v[140:143], v[104:107], v[160:163], v[140:143]
	v_mfma_f32_16x16x32_bf16 v[140:143], v[108:111], v[164:167], v[140:143]
	v_mfma_f32_16x16x32_bf16 v[132:135], v[136:139], v[164:167], v[132:135]
	v_mfma_f32_16x16x32_bf16 v[132:135], v[124:127], v[160:163], v[132:135]
	v_mfma_f32_16x16x32_bf16 v[112:115], v[124:127], v[168:171], v[112:115]
	v_mfma_f32_16x16x32_bf16 v[112:115], v[136:139], v[172:175], v[112:115]
	v_mfma_f32_16x16x32_bf16 v[116:119], v[108:111], v[172:175], v[116:119]
	v_mfma_f32_16x16x32_bf16 v[116:119], v[104:107], v[168:171], v[116:119]
	v_mfma_f32_16x16x32_bf16 v[92:95], v[104:107], v[176:179], v[92:95]
	v_mfma_f32_16x16x32_bf16 v[92:95], v[108:111], v[180:183], v[92:95]
	v_mfma_f32_16x16x32_bf16 v[88:91], v[136:139], v[180:183], v[88:91]
	v_mfma_f32_16x16x32_bf16 v[88:91], v[124:127], v[176:179], v[88:91]
	v_mfma_f32_16x16x32_bf16 v[72:75], v[124:127], v[202:205], v[72:75]
	v_mfma_f32_16x16x32_bf16 v[72:75], v[136:139], v[206:209], v[72:75]
	v_mfma_f32_16x16x32_bf16 v[76:79], v[108:111], v[206:209], v[76:79]
	v_mfma_f32_16x16x32_bf16 v[76:79], v[104:107], v[202:205], v[76:79]
	s_setprio 0
	s_setprio 1
	v_mfma_f32_16x16x32_bf16 v[128:131], v[144:147], v[160:163], v[128:131]
	v_mfma_f32_16x16x32_bf16 v[128:131], v[148:151], v[164:167], v[128:131]
	v_mfma_f32_16x16x32_bf16 v[120:123], v[156:159], v[164:167], v[120:123]
	v_mfma_f32_16x16x32_bf16 v[120:123], v[152:155], v[160:163], v[120:123]
	v_mfma_f32_16x16x32_bf16 v[96:99], v[152:155], v[168:171], v[96:99]
	v_mfma_f32_16x16x32_bf16 v[96:99], v[156:159], v[172:175], v[96:99]
	v_mfma_f32_16x16x32_bf16 v[100:103], v[148:151], v[172:175], v[100:103]
	v_mfma_f32_16x16x32_bf16 v[100:103], v[144:147], v[168:171], v[100:103]
	v_mfma_f32_16x16x32_bf16 v[84:87], v[144:147], v[176:179], v[84:87]
	v_mfma_f32_16x16x32_bf16 v[84:87], v[148:151], v[180:183], v[84:87]
	v_mfma_f32_16x16x32_bf16 v[80:83], v[156:159], v[180:183], v[80:83]
	v_mfma_f32_16x16x32_bf16 v[80:83], v[152:155], v[176:179], v[80:83]
	v_mfma_f32_16x16x32_bf16 v[64:67], v[152:155], v[202:205], v[64:67]
	v_mfma_f32_16x16x32_bf16 v[64:67], v[156:159], v[206:209], v[64:67]
	v_mfma_f32_16x16x32_bf16 v[68:71], v[148:151], v[206:209], v[68:71]
	v_mfma_f32_16x16x32_bf16 v[68:71], v[144:147], v[202:205], v[68:71]
	s_setprio 0
	s_barrier
; #define PG8_STAGE(bufoff, gbase, voff) do { _Pragma("unroll") for (int _i = 0; _i < 2; ++_i) \
;         __builtin_amdgcn_global_load_lds((const unsigned*)((const char*)(gbase) + (voff)[_i]), (PG8_LAS unsigned*)(lds + (bufoff) + ldsw + _i * 8192), 16, 0, 0); } while (0)
; #define PG8_LDA(dst, b, h) do { _Pragma("unroll") for (int m = 0; m < 4; ++m) _Pragma("unroll") for (int k = 0; k < 2; ++k) dst[m][k] = *(const PG8_LAS bf16x8*)(lds + PG8_SA(b, h) + aoff + m * 2048 + k * 1024); } while (0)
; #define PG8_MMA(ai, bj, At, Bt) do { __builtin_amdgcn_s_setprio(1); _Pragma("unroll") for (int m = 0; m < 4; ++m) _Pragma("unroll") for (int n = 0; n < 2; ++n) _Pragma("unroll") for (int k = 0; k < 2; ++k) \
;         acc[ai][bj][m][n] = __builtin_amdgcn_mfma_f32_16x16x32_bf16(Bt[n][k], At[m][k], acc[ai][bj][m][n], 0, 0, 0); __builtin_amdgcn_s_setprio(0); } while (0)
; #define PG8_WAIT_V(n) asm volatile("s_waitcnt vmcnt(" #n ")" ::: "memory")
; #define PG8_WAIT_L(n) asm volatile("s_waitcnt lgkmcnt(" #n ")" ::: "memory")
; #define PG8_BAR __builtin_amdgcn_s_barrier()
; #define PG8_SCHED __builtin_amdgcn_sched_barrier(0)
; template <class Epi, class Sched, bool ALIGN_EPI = false, bool SP2 = false>
; __device__ __forceinline__ void gemm_phase(PG8_LAS unsigned char* lds, const Gemm g, const Sched& S, const Epi& E) {
;     ...
;             PG8_LDA(At, 1, 1); PG8_STAGE(PG8_SB(1, 0), b3, voffB); PG8_STAGE(PG8_SB(1, 1), b3 + hstep, voffB); PG8_STAGE(PG8_SA(1, 0), a3, voffA);
;             PG8_WAIT_V(8); PG8_WAIT_L(0); PG8_BAR; PG8_MMA(1, 0, At, B0); PG8_MMA(1, 1, At, B1); PG8_BAR; PG8_SCHED;
;     ...
;         if constexpr (ALIGN_EPI) { if (wr == 0) PG8_BAR; }
	s_add_i32 s20, s48, s3
	v_lshl_add_u64 v[210:211], v[210:211], 0, s[14:15]
	s_mov_b32 m0, s20
	ds_read_b128 v[160:163], v224 offset:49152
	ds_read_b128 v[164:167], v224 offset:50176
	ds_read_b128 v[168:171], v224 offset:51200
	ds_read_b128 v[172:175], v224 offset:52224
	ds_read_b128 v[176:179], v224 offset:53248
	ds_read_b128 v[180:183], v224 offset:54272
	ds_read_b128 v[202:205], v224 offset:55296
	ds_read_b128 v[206:209], v224 offset:56320
	global_load_lds_dwordx4 v[210:211], off
	s_add_i32 m0, s20, 0x2000
	s_add_u32 s20, s24, 0x160080
	v_lshl_add_u64 v[210:211], v[212:213], 0, s[14:15]
	s_addc_u32 s21, s25, 0
	s_add_i32 s24, s49, s3
	global_load_lds_dwordx4 v[210:211], off
	v_lshl_add_u64 v[210:211], s[20:21], 0, v[188:189]
	s_mov_b32 m0, s24
	s_nop 0
	global_load_lds_dwordx4 v[210:211], off
	v_lshl_add_u64 v[210:211], s[20:21], 0, v[192:193]
	s_add_i32 m0, s24, 0x2000
	s_nop 0
	global_load_lds_dwordx4 v[210:211], off
	v_lshl_add_u64 v[210:211], v[214:215], 0, s[14:15]
	s_mov_b32 m0, s34
	s_nop 0
	global_load_lds_dwordx4 v[210:211], off
	v_lshl_add_u64 v[210:211], v[216:217], 0, s[14:15]
	s_mov_b32 m0, s35
	s_nop 0
	global_load_lds_dwordx4 v[210:211], off
	s_waitcnt vmcnt(8)
	s_waitcnt lgkmcnt(0)
	s_barrier
	s_setprio 1
	s_waitcnt lgkmcnt(0)
	v_mfma_f32_16x16x32_bf16 v[60:63], v[104:107], v[160:163], v[60:63]
	v_mfma_f32_16x16x32_bf16 v[60:63], v[108:111], v[164:167], v[60:63]
	v_mfma_f32_16x16x32_bf16 v[56:59], v[136:139], v[164:167], v[56:59]
	v_mfma_f32_16x16x32_bf16 v[56:59], v[124:127], v[160:163], v[56:59]
	v_mfma_f32_16x16x32_bf16 v[40:43], v[124:127], v[168:171], v[40:43]
	v_mfma_f32_16x16x32_bf16 v[40:43], v[136:139], v[172:175], v[40:43]
	v_mfma_f32_16x16x32_bf16 v[44:47], v[108:111], v[172:175], v[44:47]
	v_mfma_f32_16x16x32_bf16 v[44:47], v[104:107], v[168:171], v[44:47]
	v_mfma_f32_16x16x32_bf16 v[28:31], v[104:107], v[176:179], v[28:31]
	v_mfma_f32_16x16x32_bf16 v[28:31], v[108:111], v[180:183], v[28:31]
	v_mfma_f32_16x16x32_bf16 v[24:27], v[136:139], v[180:183], v[24:27]
	v_mfma_f32_16x16x32_bf16 v[24:27], v[124:127], v[176:179], v[24:27]
	v_mfma_f32_16x16x32_bf16 v[8:11], v[124:127], v[202:205], v[8:11]
	v_mfma_f32_16x16x32_bf16 v[8:11], v[136:139], v[206:209], v[8:11]
	v_mfma_f32_16x16x32_bf16 v[12:15], v[108:111], v[206:209], v[12:15]
	v_mfma_f32_16x16x32_bf16 v[12:15], v[104:107], v[202:205], v[12:15]
	s_setprio 0
	s_setprio 1
	v_mfma_f32_16x16x32_bf16 v[52:55], v[144:147], v[160:163], v[52:55]
	v_mfma_f32_16x16x32_bf16 v[52:55], v[148:151], v[164:167], v[52:55]
	v_mfma_f32_16x16x32_bf16 v[48:51], v[156:159], v[164:167], v[48:51]
	v_mfma_f32_16x16x32_bf16 v[48:51], v[152:155], v[160:163], v[48:51]
	v_mfma_f32_16x16x32_bf16 v[32:35], v[152:155], v[168:171], v[32:35]
	v_mfma_f32_16x16x32_bf16 v[32:35], v[156:159], v[172:175], v[32:35]
	v_mfma_f32_16x16x32_bf16 v[36:39], v[148:151], v[172:175], v[36:39]
	v_mfma_f32_16x16x32_bf16 v[36:39], v[144:147], v[168:171], v[36:39]
	v_mfma_f32_16x16x32_bf16 v[20:23], v[144:147], v[176:179], v[20:23]
	v_mfma_f32_16x16x32_bf16 v[20:23], v[148:151], v[180:183], v[20:23]
	v_mfma_f32_16x16x32_bf16 v[16:19], v[156:159], v[180:183], v[16:19]
	v_mfma_f32_16x16x32_bf16 v[16:19], v[152:155], v[176:179], v[16:19]
	v_mfma_f32_16x16x32_bf16 v[0:3], v[152:155], v[202:205], v[0:3]
	v_mfma_f32_16x16x32_bf16 v[0:3], v[156:159], v[206:209], v[0:3]
	v_mfma_f32_16x16x32_bf16 v[4:7], v[148:151], v[206:209], v[4:7]
	v_mfma_f32_16x16x32_bf16 v[4:7], v[144:147], v[202:205], v[4:7]
	s_setprio 0
	s_barrier
	s_add_i32 s47, s47, 2
	s_add_u32 s45, s45, 0x100
	s_addc_u32 s46, s46, 0
	s_cmpk_gt_u32 s47, 0x55
	s_mov_b64 s[20:21], s[22:23]
	s_cbranch_scc0 .LBB0_864
	s_and_b64 vcc, exec, s[16:17]
	s_cbranch_vccz .LBB0_867
	s_barrier
